# nt (streaming) cache hint on the f32 weight reads of all weight-conversion loops
# speedup vs baseline: 1.0175x; 1.0022x over previous
.LBB0_18:
	s_mov_b64 s[28:29], s[64:65]
	s_load_dwordx4 s[12:15], s[28:29], 0x48
	s_load_dwordx2 s[20:21], s[28:29], 0x68
	s_load_dwordx2 s[26:27], s[28:29], 0x88
	s_load_dwordx2 s[24:25], s[28:29], 0x98
	s_load_dwordx8 s[4:11], s[28:29], 0xb8
	s_load_dwordx4 s[16:19], s[28:29], 0xd8
	s_load_dwordx2 s[22:23], s[28:29], 0xf0
	v_mov_b32_e32 v1, v208
	s_mov_b32 s41, s2
	s_cmpk_gt_i32 s41, 0x3ff
	s_cbranch_scc1 .LBB0_23
	s_ashr_i32 s28, s41, 31
	s_lshr_b32 s28, s28, 28
	s_add_i32 s28, s41, s28
	s_lshl_b32 s29, s28, 2
	s_and_b32 s28, s28, 0x1fffff0
	v_ashrrev_i32_e32 v16, 6, v1
	s_sub_i32 s28, s41, s28
	s_movk_i32 s30, 0xffc0
	v_mov_b32_e32 v2, s29
	v_bfi_b32 v2, s30, v2, v1
	v_lshl_add_u32 v4, s28, 7, v16
	v_ashrrev_i32_e32 v3, 31, v2
	v_ashrrev_i32_e32 v5, 31, v4
	s_waitcnt lgkmcnt(0)
	v_lshl_add_u64 v[2:3], v[2:3], 2, s[12:13]
	v_lshlrev_b64 v[4:5], 14, v[4:5]
	v_lshl_add_u64 v[2:3], v[2:3], 0, v[4:5]
	s_mov_b32 s33, 0x20000
	v_add_co_u32_e32 v4, vcc, s33, v2
	s_mov_b32 s34, 0x40000
	s_nop 0
	v_addc_co_u32_e32 v5, vcc, 0, v3, vcc
	v_add_co_u32_e32 v6, vcc, s34, v2
	s_mov_b32 s35, 0x60000
	s_nop 0
	v_addc_co_u32_e32 v7, vcc, 0, v3, vcc
	v_add_co_u32_e32 v8, vcc, s35, v2
	s_mov_b32 s36, 0x80000
	s_nop 0
	v_addc_co_u32_e32 v9, vcc, 0, v3, vcc
	v_add_co_u32_e32 v10, vcc, s36, v2
	s_mov_b32 s37, 0xa0000
	s_nop 0
	v_addc_co_u32_e32 v11, vcc, 0, v3, vcc
	v_add_co_u32_e32 v12, vcc, s37, v2
	s_mov_b32 s38, 0xc0000
	s_nop 0
	v_addc_co_u32_e32 v13, vcc, 0, v3, vcc
	v_add_co_u32_e32 v14, vcc, s38, v2
	s_mov_b32 s39, 0xe0000
	s_nop 0
	v_addc_co_u32_e32 v15, vcc, 0, v3, vcc
	v_add_co_u32_e32 v24, vcc, s39, v2
	s_mov_b32 s40, 0x100000
	s_nop 0
	v_addc_co_u32_e32 v25, vcc, 0, v3, vcc
	v_add_co_u32_e32 v26, vcc, s40, v2
	s_mov_b32 s42, 0x120000
	s_nop 0
	v_addc_co_u32_e32 v27, vcc, 0, v3, vcc
	v_add_co_u32_e32 v28, vcc, s42, v2
	s_mov_b32 s43, 0x140000
	s_nop 0
	v_addc_co_u32_e32 v29, vcc, 0, v3, vcc
	v_add_co_u32_e32 v30, vcc, s43, v2
	s_mov_b32 s44, 0x160000
	s_nop 0
	v_addc_co_u32_e32 v31, vcc, 0, v3, vcc
	v_add_co_u32_e32 v32, vcc, s44, v2
	s_mov_b32 s45, 0x180000
	s_nop 0
	v_addc_co_u32_e32 v33, vcc, 0, v3, vcc
	v_add_co_u32_e32 v34, vcc, s45, v2
	s_mov_b32 s28, 0x1a0000
	s_nop 0
	v_addc_co_u32_e32 v35, vcc, 0, v3, vcc
	v_add_co_u32_e32 v36, vcc, s28, v2
	v_and_b32_e32 v17, 63, v1
	v_ashrrev_i32_e32 v20, 4, v1
	v_addc_co_u32_e32 v37, vcc, 0, v3, vcc
	s_mov_b32 s28, 0x1c0000
	v_lshlrev_b32_e32 v1, 3, v1
	v_add_co_u32_e32 v38, vcc, s28, v2
	v_and_b32_e32 v1, 0x78, v1
	s_nop 0
	v_addc_co_u32_e32 v39, vcc, 0, v3, vcc
	s_mov_b32 s28, 0x1e0000
	v_lshlrev_b32_e32 v18, 1, v1
	v_mov_b32_e32 v19, 0
	v_add_co_u32_e32 v40, vcc, s28, v2
	v_lshl_add_u64 v[18:19], s[22:23], 0, v[18:19]
	s_mov_b64 s[28:29], 0x378000
	v_lshl_add_u64 v[18:19], v[18:19], 0, s[28:29]
	s_movk_i32 s28, 0x104
	s_lshl_b32 s47, s60, 7
	v_addc_co_u32_e32 v41, vcc, 0, v3, vcc
	v_mul_lo_u32 v21, v16, s28
	v_mul_u32_u24_e32 v22, 0x104, v1
	v_add_u32_e32 v23, s47, v16
	global_load_dword v2, v[2:3], off nt
	s_nop 0
	global_load_dword v1, v[4:5], off nt
	s_nop 0
	global_load_dword v4, v[6:7], off nt
	global_load_dword v3, v[8:9], off nt
	s_nop 0
	global_load_dword v6, v[10:11], off nt
	global_load_dword v5, v[12:13], off nt
	global_load_dword v8, v[14:15], off nt
	global_load_dword v7, v[24:25], off nt
	s_nop 0
	global_load_dword v10, v[26:27], off nt
	global_load_dword v9, v[28:29], off nt
	global_load_dword v12, v[30:31], off nt
	global_load_dword v11, v[32:33], off nt
	global_load_dword v14, v[34:35], off nt
	global_load_dword v13, v[36:37], off nt
	global_load_dword v16, v[38:39], off nt
	global_load_dword v15, v[40:41], off nt
	s_lshl_b32 s46, s41, 7
	s_mov_b64 s[28:29], 0
	s_branch .LBB0_21

.LBB0_21:
	s_and_b64 s[30:31], s[28:29], exec
	s_cselect_b32 s30, 0x8200, 0
	s_add_i32 s49, s30, 0
	s_add_i32 s48, s41, s60
	s_cmpk_gt_i32 s48, 0x3ff
	v_lshlrev_b32_e32 v24, 2, v17
	s_cselect_b64 s[30:31], -1, 0
	v_add3_u32 v24, s49, v24, v21
	s_and_b64 vcc, exec, s[30:31]
	s_waitcnt vmcnt(15)
	ds_write_b32 v24, v2
	s_waitcnt vmcnt(14)
	ds_write_b32 v24, v1 offset:2080
	s_waitcnt vmcnt(13)
	ds_write_b32 v24, v4 offset:4160
	s_waitcnt vmcnt(12)
	ds_write_b32 v24, v3 offset:6240
	s_waitcnt vmcnt(11)
	ds_write_b32 v24, v6 offset:8320
	s_waitcnt vmcnt(10)
	ds_write_b32 v24, v5 offset:10400
	s_waitcnt vmcnt(9)
	ds_write_b32 v24, v8 offset:12480
	s_waitcnt vmcnt(8)
	ds_write_b32 v24, v7 offset:14560
	s_waitcnt vmcnt(7)
	ds_write_b32 v24, v10 offset:16640
	s_waitcnt vmcnt(6)
	ds_write_b32 v24, v9 offset:18720
	s_waitcnt vmcnt(5)
	ds_write_b32 v24, v12 offset:20800
	s_waitcnt vmcnt(4)
	ds_write_b32 v24, v11 offset:22880
	s_waitcnt vmcnt(3)
	ds_write_b32 v24, v14 offset:24960
	s_waitcnt vmcnt(2)
	ds_write_b32 v24, v13 offset:27040
	s_waitcnt vmcnt(1)
	ds_write_b32 v24, v16 offset:29120
	s_waitcnt vmcnt(0)
	ds_write_b32 v24, v15 offset:31200
	s_cbranch_vccnz .LBB0_20
	s_ashr_i32 s50, s48, 31
	s_lshr_b32 s50, s50, 28
	s_add_i32 s50, s48, s50
	s_ashr_i32 s50, s50, 4
	v_lshl_or_b32 v2, s50, 6, v17
	v_add_u32_e32 v1, s46, v23
	s_lshl_b32 s50, s50, 11
	v_subrev_u32_e32 v4, s50, v1
	v_ashrrev_i32_e32 v3, 31, v2
	v_ashrrev_i32_e32 v5, 31, v4
	v_lshl_add_u64 v[2:3], v[2:3], 2, s[12:13]
	v_lshlrev_b64 v[4:5], 14, v[4:5]
	v_lshl_add_u64 v[2:3], v[2:3], 0, v[4:5]
	v_add_co_u32_e32 v4, vcc, s33, v2
	s_nop 1
	v_addc_co_u32_e32 v5, vcc, 0, v3, vcc
	v_add_co_u32_e32 v6, vcc, s34, v2
	s_nop 1
	v_addc_co_u32_e32 v7, vcc, 0, v3, vcc
	v_add_co_u32_e32 v8, vcc, s35, v2
	s_nop 1
	v_addc_co_u32_e32 v9, vcc, 0, v3, vcc
	v_add_co_u32_e32 v10, vcc, s36, v2
	s_nop 1
	v_addc_co_u32_e32 v11, vcc, 0, v3, vcc
	v_add_co_u32_e32 v12, vcc, s37, v2
	s_nop 1
	v_addc_co_u32_e32 v13, vcc, 0, v3, vcc
	v_add_co_u32_e32 v14, vcc, s38, v2
	s_nop 1
	v_addc_co_u32_e32 v15, vcc, 0, v3, vcc
	v_add_co_u32_e32 v24, vcc, s39, v2
	s_nop 1
	v_addc_co_u32_e32 v25, vcc, 0, v3, vcc
	v_add_co_u32_e32 v26, vcc, s40, v2
	s_nop 1
	v_addc_co_u32_e32 v27, vcc, 0, v3, vcc
	v_add_co_u32_e32 v28, vcc, s42, v2
	s_nop 1
	v_addc_co_u32_e32 v29, vcc, 0, v3, vcc
	v_add_co_u32_e32 v30, vcc, s43, v2
	s_nop 1
	v_addc_co_u32_e32 v31, vcc, 0, v3, vcc
	v_add_co_u32_e32 v32, vcc, s44, v2
	s_nop 1
	v_addc_co_u32_e32 v33, vcc, 0, v3, vcc
	v_add_co_u32_e32 v34, vcc, s45, v2
	s_nop 1
	v_addc_co_u32_e32 v35, vcc, 0, v3, vcc
	v_add_co_u32_e32 v36, vcc, 0x1a0000, v2
	s_nop 1
	v_addc_co_u32_e32 v37, vcc, 0, v3, vcc
	v_add_co_u32_e32 v38, vcc, 0x1c0000, v2
	s_nop 1
	v_addc_co_u32_e32 v39, vcc, 0, v3, vcc
	v_add_co_u32_e32 v40, vcc, 0x1e0000, v2
	s_nop 1
	v_addc_co_u32_e32 v41, vcc, 0, v3, vcc
	global_load_dword v2, v[2:3], off nt
	s_nop 0
	global_load_dword v1, v[4:5], off nt
	s_nop 0
	global_load_dword v4, v[6:7], off nt
	global_load_dword v3, v[8:9], off nt
	s_nop 0
	global_load_dword v6, v[10:11], off nt
	global_load_dword v5, v[12:13], off nt
	global_load_dword v8, v[14:15], off nt
	global_load_dword v7, v[24:25], off nt
	s_nop 0
	global_load_dword v10, v[26:27], off nt
	global_load_dword v9, v[28:29], off nt
	global_load_dword v12, v[30:31], off nt
	global_load_dword v11, v[32:33], off nt
	global_load_dword v14, v[34:35], off nt
	global_load_dword v13, v[36:37], off nt
	global_load_dword v16, v[38:39], off nt
	global_load_dword v15, v[40:41], off nt
	s_branch .LBB0_20

.LBB0_30:
	s_waitcnt vmcnt(16)
	v_mov_b32_e32 v1, v208
	s_mov_b32 s52, s2
	s_cmpk_gt_i32 s52, 0x7f
	s_cbranch_scc1 .LBB0_29
	s_lshl_b64 s[12:13], s[6:7], 22
	s_add_u32 s12, s4, s12
	s_addc_u32 s13, s5, s13
	s_lshl_b64 s[28:29], s[6:7], 21
	s_add_u32 s28, s33, s28
	s_addc_u32 s29, s34, s29
	s_ashr_i32 s30, s52, 31
	s_lshr_b32 s30, s30, 30
	s_add_i32 s30, s52, s30
	s_lshl_b32 s31, s30, 4
	s_and_b32 s30, s30, 0x1fffffc
	v_ashrrev_i32_e32 v24, 6, v1
	s_sub_i32 s30, s52, s30
	v_mov_b32_e32 v2, s31
	v_bfi_b32 v2, s35, v2, v1
	s_waitcnt vmcnt(15)
	v_lshl_add_u32 v4, s30, 7, v24
	s_waitcnt vmcnt(14)
	v_ashrrev_i32_e32 v3, 31, v2
	s_waitcnt vmcnt(12)
	v_ashrrev_i32_e32 v5, 31, v4
	v_lshl_add_u64 v[2:3], v[2:3], 2, s[12:13]
	v_lshlrev_b64 v[4:5], 13, v[4:5]
	v_lshl_add_u64 v[2:3], v[2:3], 0, v[4:5]
	v_add_co_u32_e32 v4, vcc, s36, v2
	v_and_b32_e32 v20, 63, v1
	s_nop 0
	v_addc_co_u32_e32 v5, vcc, 0, v3, vcc
	v_add_co_u32_e32 v6, vcc, s37, v2
	v_ashrrev_i32_e32 v21, 4, v1
	s_waitcnt vmcnt(10)
	v_addc_co_u32_e32 v7, vcc, 0, v3, vcc
	v_add_co_u32_e32 v8, vcc, s38, v2
	v_lshlrev_b32_e32 v1, 3, v1
	s_waitcnt vmcnt(8)
	v_addc_co_u32_e32 v9, vcc, 0, v3, vcc
	v_add_co_u32_e32 v10, vcc, s39, v2
	v_and_b32_e32 v1, 0x78, v1
	s_waitcnt vmcnt(6)
	v_addc_co_u32_e32 v11, vcc, 0, v3, vcc
	v_add_co_u32_e32 v12, vcc, s40, v2
	s_waitcnt vmcnt(3)
	v_lshlrev_b32_e32 v16, 1, v1
	v_addc_co_u32_e32 v13, vcc, 0, v3, vcc
	v_add_co_u32_e32 v14, vcc, s41, v2
	s_load_dword s53, s[62:63], 0x0
	s_load_dword s30, s[62:63], 0x10
	s_waitcnt vmcnt(2)
	v_addc_co_u32_e32 v15, vcc, 0, v3, vcc
	v_add_co_u32_e32 v26, vcc, s42, v2
	v_lshl_add_u64 v[18:19], s[28:29], 0, v[16:17]
	s_nop 0
	v_addc_co_u32_e32 v27, vcc, 0, v3, vcc
	v_add_co_u32_e32 v28, vcc, s43, v2
	v_mul_u32_u24_e32 v23, 0x104, v1
	s_nop 0
	v_addc_co_u32_e32 v29, vcc, 0, v3, vcc
	v_add_co_u32_e32 v30, vcc, s44, v2
	s_waitcnt lgkmcnt(0)
	s_lshr_b32 s30, s30, 16
	v_addc_co_u32_e32 v31, vcc, 0, v3, vcc
	v_add_co_u32_e32 v32, vcc, s45, v2
	s_cmp_lg_u32 s30, 0
	s_nop 0
	v_addc_co_u32_e32 v33, vcc, 0, v3, vcc
	v_add_co_u32_e32 v34, vcc, s46, v2
	s_cselect_b64 s[30:31], -1, 0
	s_nop 0
	v_addc_co_u32_e32 v35, vcc, 0, v3, vcc
	v_add_co_u32_e32 v36, vcc, s47, v2
	s_cmp_lg_u64 s[30:31], 0
	s_nop 0
	v_addc_co_u32_e32 v37, vcc, 0, v3, vcc
	v_add_co_u32_e32 v38, vcc, s48, v2
	s_addc_u32 s53, s53, 0
	s_nop 0
	v_addc_co_u32_e32 v39, vcc, 0, v3, vcc
	v_add_co_u32_e32 v40, vcc, s49, v2
	s_lshl_b32 s55, s53, 7
	s_nop 0
	v_addc_co_u32_e32 v41, vcc, 0, v3, vcc
	v_add_co_u32_e32 v42, vcc, s50, v2
	v_mul_lo_u32 v22, v24, s51
	s_nop 0
	v_addc_co_u32_e32 v43, vcc, 0, v3, vcc
	global_load_dword v2, v[2:3], off nt
	s_nop 0
	global_load_dword v1, v[4:5], off nt
	s_nop 0
	global_load_dword v4, v[6:7], off nt
	global_load_dword v3, v[8:9], off nt
	s_nop 0
	global_load_dword v6, v[10:11], off nt
	global_load_dword v5, v[12:13], off nt
	global_load_dword v8, v[14:15], off nt
	global_load_dword v7, v[26:27], off nt
	s_nop 0
	global_load_dword v10, v[28:29], off nt
	global_load_dword v9, v[30:31], off nt
	global_load_dword v12, v[32:33], off nt
	global_load_dword v11, v[34:35], off nt
	global_load_dword v14, v[36:37], off nt
	global_load_dword v13, v[38:39], off nt
	global_load_dword v16, v[40:41], off nt
	global_load_dword v15, v[42:43], off nt
	s_lshl_b32 s54, s52, 7
	v_add_u32_e32 v24, s55, v24
	s_mov_b64 s[28:29], 0
	s_branch .LBB0_33

.LBB0_33:
	s_and_b64 s[30:31], s[28:29], exec
	s_cselect_b32 s30, 0x8200, 0
	s_add_i32 s57, s30, 0
	s_add_i32 s56, s53, s52
	s_cmpk_gt_i32 s56, 0x7f
	v_lshlrev_b32_e32 v25, 2, v20
	s_cselect_b64 s[30:31], -1, 0
	v_add3_u32 v25, s57, v25, v22
	s_and_b64 vcc, exec, s[30:31]
	s_waitcnt vmcnt(15)
	ds_write_b32 v25, v2
	s_waitcnt vmcnt(14)
	ds_write_b32 v25, v1 offset:2080
	s_waitcnt vmcnt(13)
	ds_write_b32 v25, v4 offset:4160
	s_waitcnt vmcnt(12)
	ds_write_b32 v25, v3 offset:6240
	s_waitcnt vmcnt(11)
	ds_write_b32 v25, v6 offset:8320
	s_waitcnt vmcnt(10)
	ds_write_b32 v25, v5 offset:10400
	s_waitcnt vmcnt(9)
	ds_write_b32 v25, v8 offset:12480
	s_waitcnt vmcnt(8)
	ds_write_b32 v25, v7 offset:14560
	s_waitcnt vmcnt(7)
	ds_write_b32 v25, v10 offset:16640
	s_waitcnt vmcnt(6)
	ds_write_b32 v25, v9 offset:18720
	s_waitcnt vmcnt(5)
	ds_write_b32 v25, v12 offset:20800
	s_waitcnt vmcnt(4)
	ds_write_b32 v25, v11 offset:22880
	s_waitcnt vmcnt(3)
	ds_write_b32 v25, v14 offset:24960
	s_waitcnt vmcnt(2)
	ds_write_b32 v25, v13 offset:27040
	s_waitcnt vmcnt(1)
	ds_write_b32 v25, v16 offset:29120
	s_waitcnt vmcnt(0)
	ds_write_b32 v25, v15 offset:31200
	s_cbranch_vccnz .LBB0_32
	s_ashr_i32 s58, s56, 31
	s_lshr_b32 s58, s58, 30
	s_add_i32 s58, s56, s58
	s_ashr_i32 s58, s58, 2
	v_lshl_or_b32 v2, s58, 6, v20
	v_add_u32_e32 v1, s54, v24
	s_lshl_b32 s58, s58, 9
	v_subrev_u32_e32 v4, s58, v1
	v_ashrrev_i32_e32 v3, 31, v2
	v_ashrrev_i32_e32 v5, 31, v4
	v_lshl_add_u64 v[2:3], v[2:3], 2, s[12:13]
	v_lshlrev_b64 v[4:5], 13, v[4:5]
	v_lshl_add_u64 v[2:3], v[2:3], 0, v[4:5]
	v_add_co_u32_e32 v4, vcc, s36, v2
	s_nop 1
	v_addc_co_u32_e32 v5, vcc, 0, v3, vcc
	v_add_co_u32_e32 v6, vcc, s37, v2
	s_nop 1
	v_addc_co_u32_e32 v7, vcc, 0, v3, vcc
	v_add_co_u32_e32 v8, vcc, s38, v2
	s_nop 1
	v_addc_co_u32_e32 v9, vcc, 0, v3, vcc
	v_add_co_u32_e32 v10, vcc, s39, v2
	s_nop 1
	v_addc_co_u32_e32 v11, vcc, 0, v3, vcc
	v_add_co_u32_e32 v12, vcc, s40, v2
	s_nop 1
	v_addc_co_u32_e32 v13, vcc, 0, v3, vcc
	v_add_co_u32_e32 v14, vcc, s41, v2
	s_nop 1
	v_addc_co_u32_e32 v15, vcc, 0, v3, vcc
	v_add_co_u32_e32 v26, vcc, s42, v2
	s_nop 1
	v_addc_co_u32_e32 v27, vcc, 0, v3, vcc
	v_add_co_u32_e32 v28, vcc, s43, v2
	s_nop 1
	v_addc_co_u32_e32 v29, vcc, 0, v3, vcc
	v_add_co_u32_e32 v30, vcc, s44, v2
	s_nop 1
	v_addc_co_u32_e32 v31, vcc, 0, v3, vcc
	v_add_co_u32_e32 v32, vcc, s45, v2
	s_nop 1
	v_addc_co_u32_e32 v33, vcc, 0, v3, vcc
	v_add_co_u32_e32 v34, vcc, s46, v2
	s_nop 1
	v_addc_co_u32_e32 v35, vcc, 0, v3, vcc
	v_add_co_u32_e32 v36, vcc, s47, v2
	s_nop 1
	v_addc_co_u32_e32 v37, vcc, 0, v3, vcc
	v_add_co_u32_e32 v38, vcc, 0xd0000, v2
	s_nop 1
	v_addc_co_u32_e32 v39, vcc, 0, v3, vcc
	v_add_co_u32_e32 v40, vcc, 0xe0000, v2
	s_nop 1
	v_addc_co_u32_e32 v41, vcc, 0, v3, vcc
	v_add_co_u32_e32 v42, vcc, 0xf0000, v2
	s_nop 1
	v_addc_co_u32_e32 v43, vcc, 0, v3, vcc
	global_load_dword v2, v[2:3], off nt
	s_nop 0
	global_load_dword v1, v[4:5], off nt
	s_nop 0
	global_load_dword v4, v[6:7], off nt
	global_load_dword v3, v[8:9], off nt
	s_nop 0
	global_load_dword v6, v[10:11], off nt
	global_load_dword v5, v[12:13], off nt
	global_load_dword v8, v[14:15], off nt
	global_load_dword v7, v[26:27], off nt
	s_nop 0
	global_load_dword v10, v[28:29], off nt
	global_load_dword v9, v[30:31], off nt
	global_load_dword v12, v[32:33], off nt
	global_load_dword v11, v[34:35], off nt
	global_load_dword v14, v[36:37], off nt
	global_load_dword v13, v[38:39], off nt
	global_load_dword v16, v[40:41], off nt
	global_load_dword v15, v[42:43], off nt
	s_branch .LBB0_32
.LBB0_35:
	s_waitcnt vmcnt(16)
	v_mov_b32_e32 v1, v208
	s_mov_b32 s35, s2
	s_cmpk_gt_i32 s35, 0x1ff
	s_cbranch_scc1 .LBB0_40
	s_ashr_i32 s4, s35, 31
	s_lshr_b32 s4, s4, 28
	s_add_i32 s4, s35, s4
	s_lshl_b32 s5, s4, 2
	s_and_b32 s4, s4, 0x1fffff0
	s_waitcnt vmcnt(3)
	v_ashrrev_i32_e32 v16, 6, v1
	s_sub_i32 s4, s35, s4
	s_movk_i32 s6, 0xffc0
	v_mov_b32_e32 v2, s5
	v_bfi_b32 v2, s6, v2, v1
	v_lshl_add_u32 v4, s4, 7, v16
	v_ashrrev_i32_e32 v3, 31, v2
	v_ashrrev_i32_e32 v5, 31, v4
	v_lshl_add_u64 v[2:3], v[2:3], 2, s[8:9]
	v_lshlrev_b64 v[4:5], 13, v[4:5]
	v_lshl_add_u64 v[2:3], v[2:3], 0, v[4:5]
	s_mov_b32 s12, 0x10000
	v_add_co_u32_e32 v4, vcc, s12, v2
	s_mov_b32 s13, 0x20000
	s_nop 0
	v_addc_co_u32_e32 v5, vcc, 0, v3, vcc
	v_add_co_u32_e32 v6, vcc, s13, v2
	s_mov_b32 s28, 0x30000
	s_nop 0
	v_addc_co_u32_e32 v7, vcc, 0, v3, vcc
	v_add_co_u32_e32 v8, vcc, s28, v2
	s_mov_b32 s29, 0x40000
	s_nop 0
	v_addc_co_u32_e32 v9, vcc, 0, v3, vcc
	v_add_co_u32_e32 v10, vcc, s29, v2
	s_mov_b32 s30, 0x50000
	s_nop 0
	v_addc_co_u32_e32 v11, vcc, 0, v3, vcc
	v_add_co_u32_e32 v12, vcc, s30, v2
	s_mov_b32 s31, 0x60000
	s_nop 0
	v_addc_co_u32_e32 v13, vcc, 0, v3, vcc
	v_add_co_u32_e32 v14, vcc, s31, v2
	s_mov_b32 s33, 0x70000
	s_waitcnt vmcnt(2)
	v_addc_co_u32_e32 v15, vcc, 0, v3, vcc
	v_add_co_u32_e32 v24, vcc, s33, v2
	s_mov_b32 s34, 0x80000
	s_nop 0
	v_addc_co_u32_e32 v25, vcc, 0, v3, vcc
	v_add_co_u32_e32 v26, vcc, s34, v2
	s_mov_b32 s36, 0x90000
	s_nop 0
	v_addc_co_u32_e32 v27, vcc, 0, v3, vcc
	v_add_co_u32_e32 v28, vcc, s36, v2
	s_mov_b32 s37, 0xa0000
	s_nop 0
	v_addc_co_u32_e32 v29, vcc, 0, v3, vcc
	v_add_co_u32_e32 v30, vcc, s37, v2
	s_mov_b32 s38, 0xb0000
	s_nop 0
	v_addc_co_u32_e32 v31, vcc, 0, v3, vcc
	v_add_co_u32_e32 v32, vcc, s38, v2
	s_mov_b32 s39, 0xc0000
	s_nop 0
	v_addc_co_u32_e32 v33, vcc, 0, v3, vcc
	v_add_co_u32_e32 v34, vcc, s39, v2
	s_mov_b32 s4, 0xd0000
	s_nop 0
	v_addc_co_u32_e32 v35, vcc, 0, v3, vcc
	s_load_dword s6, s[62:63], 0x0
	s_load_dword s5, s[62:63], 0x10
	v_add_co_u32_e32 v36, vcc, s4, v2
	s_mov_b32 s4, 0xe0000
	s_nop 0
	v_addc_co_u32_e32 v37, vcc, 0, v3, vcc
	v_add_co_u32_e32 v38, vcc, s4, v2
	s_mov_b32 s4, 0xf0000
	s_nop 0
	v_addc_co_u32_e32 v39, vcc, 0, v3, vcc
	v_add_co_u32_e32 v40, vcc, s4, v2
	s_waitcnt lgkmcnt(0)
	s_lshr_b32 s4, s5, 16
	v_and_b32_e32 v17, 63, v1
	v_ashrrev_i32_e32 v20, 4, v1
	s_cmp_lg_u32 s4, 0
	v_lshlrev_b32_e32 v1, 3, v1
	s_cselect_b64 s[4:5], -1, 0
	v_and_b32_e32 v1, 0x78, v1
	s_cmp_lg_u64 s[4:5], 0
	v_lshlrev_b32_e32 v18, 1, v1
	v_mov_b32_e32 v19, 0
	s_addc_u32 s40, s6, 0
	v_lshl_add_u64 v[18:19], s[22:23], 0, v[18:19]
	s_mov_b64 s[4:5], 0x3b78000
	v_lshl_add_u64 v[18:19], v[18:19], 0, s[4:5]
	s_movk_i32 s4, 0x104
	s_lshl_b32 s42, s40, 7
	v_addc_co_u32_e32 v41, vcc, 0, v3, vcc
	v_mul_lo_u32 v21, v16, s4
	v_mul_u32_u24_e32 v22, 0x104, v1
	v_add_u32_e32 v23, s42, v16
	global_load_dword v2, v[2:3], off nt
	s_nop 0
	global_load_dword v1, v[4:5], off nt
	s_nop 0
	global_load_dword v4, v[6:7], off nt
	global_load_dword v3, v[8:9], off nt
	s_nop 0
	global_load_dword v6, v[10:11], off nt
	global_load_dword v5, v[12:13], off nt
	global_load_dword v8, v[14:15], off nt
	global_load_dword v7, v[24:25], off nt
	s_nop 0
	global_load_dword v10, v[26:27], off nt
	global_load_dword v9, v[28:29], off nt
	global_load_dword v12, v[30:31], off nt
	global_load_dword v11, v[32:33], off nt
	global_load_dword v14, v[34:35], off nt
	global_load_dword v13, v[36:37], off nt
	global_load_dword v16, v[38:39], off nt
	global_load_dword v15, v[40:41], off nt
	s_lshl_b32 s41, s35, 7
	s_mov_b64 s[4:5], 0
	s_branch .LBB0_38

.LBB0_38:
	s_and_b64 s[6:7], s[4:5], exec
	s_cselect_b32 s6, 0x8200, 0
	s_add_i32 s44, s6, 0
	s_add_i32 s43, s40, s35
	s_cmpk_gt_i32 s43, 0x1ff
	v_lshlrev_b32_e32 v24, 2, v17
	s_cselect_b64 s[6:7], -1, 0
	v_add3_u32 v24, s44, v24, v21
	s_and_b64 vcc, exec, s[6:7]
	s_waitcnt vmcnt(15)
	ds_write_b32 v24, v2
	s_waitcnt vmcnt(14)
	ds_write_b32 v24, v1 offset:2080
	s_waitcnt vmcnt(13)
	ds_write_b32 v24, v4 offset:4160
	s_waitcnt vmcnt(12)
	ds_write_b32 v24, v3 offset:6240
	s_waitcnt vmcnt(11)
	ds_write_b32 v24, v6 offset:8320
	s_waitcnt vmcnt(10)
	ds_write_b32 v24, v5 offset:10400
	s_waitcnt vmcnt(9)
	ds_write_b32 v24, v8 offset:12480
	s_waitcnt vmcnt(8)
	ds_write_b32 v24, v7 offset:14560
	s_waitcnt vmcnt(7)
	ds_write_b32 v24, v10 offset:16640
	s_waitcnt vmcnt(6)
	ds_write_b32 v24, v9 offset:18720
	s_waitcnt vmcnt(5)
	ds_write_b32 v24, v12 offset:20800
	s_waitcnt vmcnt(4)
	ds_write_b32 v24, v11 offset:22880
	s_waitcnt vmcnt(3)
	ds_write_b32 v24, v14 offset:24960
	s_waitcnt vmcnt(2)
	ds_write_b32 v24, v13 offset:27040
	s_waitcnt vmcnt(1)
	ds_write_b32 v24, v16 offset:29120
	s_waitcnt vmcnt(0)
	ds_write_b32 v24, v15 offset:31200
	s_cbranch_vccnz .LBB0_37
	s_ashr_i32 s45, s43, 31
	s_lshr_b32 s45, s45, 28
	s_add_i32 s45, s43, s45
	s_ashr_i32 s45, s45, 4
	v_lshl_or_b32 v2, s45, 6, v17
	v_add_u32_e32 v1, s41, v23
	s_lshl_b32 s45, s45, 11
	v_subrev_u32_e32 v4, s45, v1
	v_ashrrev_i32_e32 v3, 31, v2
	v_ashrrev_i32_e32 v5, 31, v4
	v_lshl_add_u64 v[2:3], v[2:3], 2, s[8:9]
	v_lshlrev_b64 v[4:5], 13, v[4:5]
	v_lshl_add_u64 v[2:3], v[2:3], 0, v[4:5]
	v_add_co_u32_e32 v4, vcc, s12, v2
	s_nop 1
	v_addc_co_u32_e32 v5, vcc, 0, v3, vcc
	v_add_co_u32_e32 v6, vcc, s13, v2
	s_nop 1
	v_addc_co_u32_e32 v7, vcc, 0, v3, vcc
	v_add_co_u32_e32 v8, vcc, s28, v2
	s_nop 1
	v_addc_co_u32_e32 v9, vcc, 0, v3, vcc
	v_add_co_u32_e32 v10, vcc, s29, v2
	s_nop 1
	v_addc_co_u32_e32 v11, vcc, 0, v3, vcc
	v_add_co_u32_e32 v12, vcc, s30, v2
	s_nop 1
	v_addc_co_u32_e32 v13, vcc, 0, v3, vcc
	v_add_co_u32_e32 v14, vcc, s31, v2
	s_nop 1
	v_addc_co_u32_e32 v15, vcc, 0, v3, vcc
	v_add_co_u32_e32 v24, vcc, s33, v2
	s_nop 1
	v_addc_co_u32_e32 v25, vcc, 0, v3, vcc
	v_add_co_u32_e32 v26, vcc, s34, v2
	s_nop 1
	v_addc_co_u32_e32 v27, vcc, 0, v3, vcc
	v_add_co_u32_e32 v28, vcc, s36, v2
	s_nop 1
	v_addc_co_u32_e32 v29, vcc, 0, v3, vcc
	v_add_co_u32_e32 v30, vcc, s37, v2
	s_nop 1
	v_addc_co_u32_e32 v31, vcc, 0, v3, vcc
	v_add_co_u32_e32 v32, vcc, s38, v2
	s_nop 1
	v_addc_co_u32_e32 v33, vcc, 0, v3, vcc
	v_add_co_u32_e32 v34, vcc, s39, v2
	s_nop 1
	v_addc_co_u32_e32 v35, vcc, 0, v3, vcc
	v_add_co_u32_e32 v36, vcc, 0xd0000, v2
	s_nop 1
	v_addc_co_u32_e32 v37, vcc, 0, v3, vcc
	v_add_co_u32_e32 v38, vcc, 0xe0000, v2
	s_nop 1
	v_addc_co_u32_e32 v39, vcc, 0, v3, vcc
	v_add_co_u32_e32 v40, vcc, 0xf0000, v2
	s_nop 1
	v_addc_co_u32_e32 v41, vcc, 0, v3, vcc
	global_load_dword v2, v[2:3], off nt
	s_nop 0
	global_load_dword v1, v[4:5], off nt
	s_nop 0
	global_load_dword v4, v[6:7], off nt
	global_load_dword v3, v[8:9], off nt
	s_nop 0
	global_load_dword v6, v[10:11], off nt
	global_load_dword v5, v[12:13], off nt
	global_load_dword v8, v[14:15], off nt
	global_load_dword v7, v[24:25], off nt
	s_nop 0
	global_load_dword v10, v[26:27], off nt
	global_load_dword v9, v[28:29], off nt
	global_load_dword v12, v[30:31], off nt
	global_load_dword v11, v[32:33], off nt
	global_load_dword v14, v[34:35], off nt
	global_load_dword v13, v[36:37], off nt
	global_load_dword v16, v[38:39], off nt
	global_load_dword v15, v[40:41], off nt
	s_branch .LBB0_37

.LBB0_52:
	s_waitcnt vmcnt(16)
	v_mov_b32_e32 v1, v208
	s_lshl_b32 s31, s4, 1
	s_sub_i32 s31, s2, s31
	s_sub_i32 s31, s31, 128
	s_cmp_gt_u32 s31, 1
	s_cbranch_scc1 .LBB0_51
	s_lshl_b64 s[6:7], s[4:5], 16
	s_add_u32 s6, s14, s6
	s_addc_u32 s7, s15, s7
	s_lshl_b64 s[8:9], s[4:5], 15
	s_add_u32 s8, s12, s8
	v_and_b32_e32 v22, 63, v1
	s_addc_u32 s9, s13, s9
	s_lshl_b32 s33, s31, 6
	v_ashrrev_i32_e32 v2, 6, v1
	s_waitcnt vmcnt(15)
	v_or_b32_e32 v4, s33, v22
	s_waitcnt vmcnt(12)
	v_ashrrev_i32_e32 v5, 31, v4
	v_ashrrev_i32_e32 v3, 31, v2
	v_lshl_add_u64 v[4:5], v[4:5], 2, s[6:7]
	s_waitcnt vmcnt(10)
	v_lshlrev_b64 v[6:7], 9, v[2:3]
	v_lshl_add_u64 v[28:29], v[4:5], 0, v[6:7]
	v_add_co_u32_e32 v30, vcc, s10, v28
	s_load_dword s36, s[62:63], 0x0
	s_load_dword s34, s[62:63], 0x10
	v_addc_co_u32_e32 v31, vcc, 0, v29, vcc
	v_add_co_u32_e32 v32, vcc, s11, v28
	s_waitcnt lgkmcnt(0)
	s_lshr_b32 s34, s34, 16
	v_addc_co_u32_e32 v33, vcc, 0, v29, vcc
	v_add_co_u32_e32 v34, vcc, s16, v28
	s_cmp_lg_u32 s34, 0
	s_nop 0
	v_addc_co_u32_e32 v35, vcc, 0, v29, vcc
	v_add_co_u32_e32 v36, vcc, s17, v28
	v_ashrrev_i32_e32 v23, 4, v1
	s_nop 0
	v_addc_co_u32_e32 v37, vcc, 0, v29, vcc
	v_add_co_u32_e32 v38, vcc, s18, v28
	s_cselect_b64 s[34:35], -1, 0
	s_nop 0
	v_addc_co_u32_e32 v39, vcc, 0, v29, vcc
	v_add_co_u32_e32 v40, vcc, s19, v28
	v_lshlrev_b32_e32 v1, 3, v1
	s_nop 0
	v_addc_co_u32_e32 v41, vcc, 0, v29, vcc
	v_add_co_u32_e32 v42, vcc, s28, v28
	v_cndmask_b32_e64 v3, 0, 1, s[34:35]
	s_cmp_lg_u64 s[34:35], 0
	v_and_b32_e32 v1, 0x78, v1
	v_addc_co_u32_e32 v43, vcc, 0, v29, vcc
	s_addc_u32 s34, s36, 0
	s_waitcnt vmcnt(3)
	v_lshlrev_b32_e32 v16, 1, v1
	v_mul_u32_u24_e32 v25, 0x104, v1
	v_lshl_add_u64 v[20:21], s[6:7], 0, v[6:7]
	s_lshl_b32 s6, s36, 6
	v_lshlrev_b32_e32 v1, 6, v3
	v_add_co_u32_e32 v44, vcc, s29, v28
	v_add_u32_e32 v1, s6, v1
	s_nop 0
	v_addc_co_u32_e32 v45, vcc, 0, v29, vcc
	v_lshl_add_u64 v[18:19], s[8:9], 0, v[16:17]
	v_mul_lo_u32 v24, v2, s30
	v_or_b32_e32 v26, v1, v22
	global_load_dword v7, v[36:37], off offset:-4096 nt
	global_load_dword v8, v[36:37], off nt
	global_load_dword v9, v[38:39], off offset:-4096 nt
	global_load_dword v10, v[38:39], off nt
	global_load_dword v11, v[40:41], off offset:-4096 nt
	global_load_dword v12, v[40:41], off nt
	global_load_dword v13, v[42:43], off offset:-4096 nt
	global_load_dword v16, v[42:43], off nt
	global_load_dword v2, v[28:29], off nt
	global_load_dword v1, v[30:31], off offset:-4096 nt
	global_load_dword v4, v[30:31], off nt
	global_load_dword v3, v[32:33], off offset:-4096 nt
	global_load_dword v6, v[32:33], off nt
	global_load_dword v5, v[34:35], off offset:-4096 nt
	global_load_dword v14, v[34:35], off nt
	global_load_dword v15, v[44:45], off nt
	s_lshl_b32 s35, s34, 6
	s_mov_b64 s[6:7], 0
	s_branch .LBB0_55

.LBB0_55:
	s_and_b64 s[8:9], s[6:7], exec
	s_cselect_b32 s8, 0x8200, 0
	s_add_i32 s36, s8, 0
	s_add_i32 s31, s34, s31
	s_cmp_gt_i32 s31, 1
	v_lshlrev_b32_e32 v27, 2, v22
	s_cselect_b64 s[8:9], -1, 0
	v_add3_u32 v27, s36, v27, v24
	s_and_b64 vcc, exec, s[8:9]
	s_waitcnt vmcnt(7)
	ds_write_b32 v27, v2
	s_waitcnt vmcnt(6)
	ds_write_b32 v27, v1 offset:2080
	s_waitcnt vmcnt(5)
	ds_write_b32 v27, v4 offset:4160
	s_waitcnt vmcnt(4)
	ds_write_b32 v27, v3 offset:6240
	s_waitcnt vmcnt(3)
	ds_write_b32 v27, v6 offset:8320
	s_waitcnt vmcnt(2)
	ds_write_b32 v27, v5 offset:10400
	s_waitcnt vmcnt(1)
	ds_write_b32 v27, v14 offset:12480
	ds_write_b32 v27, v7 offset:14560
	ds_write_b32 v27, v8 offset:16640
	ds_write_b32 v27, v9 offset:18720
	ds_write_b32 v27, v10 offset:20800
	ds_write_b32 v27, v11 offset:22880
	ds_write_b32 v27, v12 offset:24960
	ds_write_b32 v27, v13 offset:27040
	ds_write_b32 v27, v16 offset:29120
	s_waitcnt vmcnt(0)
	ds_write_b32 v27, v15 offset:31200
	s_cbranch_vccnz .LBB0_54
	v_add_u32_e32 v2, s33, v26
	v_ashrrev_i32_e32 v3, 31, v2
	v_lshl_add_u64 v[28:29], v[2:3], 2, v[20:21]
	v_add_co_u32_e32 v30, vcc, 0x1000, v28
	s_nop 1
	v_addc_co_u32_e32 v31, vcc, 0, v29, vcc
	v_add_co_u32_e32 v32, vcc, 0x2000, v28
	s_nop 1
	v_addc_co_u32_e32 v33, vcc, 0, v29, vcc
	v_add_co_u32_e32 v34, vcc, 0x3000, v28
	s_nop 1
	v_addc_co_u32_e32 v35, vcc, 0, v29, vcc
	v_add_co_u32_e32 v36, vcc, 0x4000, v28
	s_nop 1
	v_addc_co_u32_e32 v37, vcc, 0, v29, vcc
	v_add_co_u32_e32 v38, vcc, 0x5000, v28
	s_nop 1
	v_addc_co_u32_e32 v39, vcc, 0, v29, vcc
	v_add_co_u32_e32 v40, vcc, 0x6000, v28
	s_nop 1
	v_addc_co_u32_e32 v41, vcc, 0, v29, vcc
	v_add_co_u32_e32 v42, vcc, 0x7000, v28
	s_nop 1
	v_addc_co_u32_e32 v43, vcc, 0, v29, vcc
	v_add_co_u32_e32 v44, vcc, 0x8000, v28
	s_nop 1
	v_addc_co_u32_e32 v45, vcc, 0, v29, vcc
	v_add_co_u32_e32 v46, vcc, 0x9000, v28
	s_nop 1
	v_addc_co_u32_e32 v47, vcc, 0, v29, vcc
	v_add_co_u32_e32 v48, vcc, 0xa000, v28
	s_nop 1
	v_addc_co_u32_e32 v49, vcc, 0, v29, vcc
	v_add_co_u32_e32 v50, vcc, 0xb000, v28
	s_nop 1
	v_addc_co_u32_e32 v51, vcc, 0, v29, vcc
	v_add_co_u32_e32 v52, vcc, 0xc000, v28
	s_nop 1
	v_addc_co_u32_e32 v53, vcc, 0, v29, vcc
	v_add_co_u32_e32 v54, vcc, 0xd000, v28
	s_nop 1
	v_addc_co_u32_e32 v55, vcc, 0, v29, vcc
	v_add_co_u32_e32 v56, vcc, 0xe000, v28
	s_nop 1
	v_addc_co_u32_e32 v57, vcc, 0, v29, vcc
	v_add_co_u32_e32 v58, vcc, 0xf000, v28
	s_nop 1
	v_addc_co_u32_e32 v59, vcc, 0, v29, vcc
	global_load_dword v2, v[28:29], off nt
	global_load_dword v1, v[30:31], off nt
	global_load_dword v4, v[32:33], off nt
	global_load_dword v3, v[34:35], off nt
	global_load_dword v6, v[36:37], off nt
	global_load_dword v5, v[38:39], off nt
	global_load_dword v14, v[40:41], off nt
	global_load_dword v7, v[42:43], off nt
	global_load_dword v8, v[44:45], off nt
	global_load_dword v9, v[46:47], off nt
	global_load_dword v10, v[48:49], off nt
	global_load_dword v11, v[50:51], off nt
	global_load_dword v12, v[52:53], off nt
	global_load_dword v13, v[54:55], off nt
	global_load_dword v16, v[56:57], off nt
	global_load_dword v15, v[58:59], off nt
	s_branch .LBB0_54

.LBB0_59:
	s_waitcnt vmcnt(16)
	v_mov_b32_e32 v1, v208
	s_lshl_b32 s33, s31, 1
	s_sub_i32 s33, s2, s33
	s_sub_i32 s33, s33, 136
	s_cmp_gt_u32 s33, 1
	s_cbranch_scc1 .LBB0_58
	s_lshl_b32 s4, s31, 14
	s_lshl_b64 s[8:9], s[4:5], 2
	s_add_u32 s8, s26, s8
	s_addc_u32 s9, s27, s9
	s_lshl_b32 s4, s31, 15
	s_add_u32 s10, s12, s4
	v_and_b32_e32 v22, 63, v1
	s_addc_u32 s11, s13, 0
	s_lshl_b32 s4, s33, 6
	v_ashrrev_i32_e32 v2, 6, v1
	s_waitcnt vmcnt(15)
	v_or_b32_e32 v4, s4, v22
	s_waitcnt vmcnt(12)
	v_ashrrev_i32_e32 v5, 31, v4
	v_ashrrev_i32_e32 v3, 31, v2
	v_lshl_add_u64 v[4:5], v[4:5], 2, s[8:9]
	s_waitcnt vmcnt(10)
	v_lshlrev_b64 v[6:7], 9, v[2:3]
	v_lshl_add_u64 v[28:29], v[4:5], 0, v[6:7]
	v_add_co_u32_e32 v30, vcc, s14, v28
	s_load_dword s36, s[62:63], 0x0
	s_load_dword s34, s[62:63], 0x10
	v_addc_co_u32_e32 v31, vcc, 0, v29, vcc
	v_add_co_u32_e32 v32, vcc, s15, v28
	s_waitcnt lgkmcnt(0)
	s_lshr_b32 s34, s34, 16
	v_addc_co_u32_e32 v33, vcc, 0, v29, vcc
	v_add_co_u32_e32 v34, vcc, s16, v28
	s_cmp_lg_u32 s34, 0
	s_nop 0
	v_addc_co_u32_e32 v35, vcc, 0, v29, vcc
	v_add_co_u32_e32 v36, vcc, s17, v28
	v_ashrrev_i32_e32 v23, 4, v1
	s_nop 0
	v_addc_co_u32_e32 v37, vcc, 0, v29, vcc
	v_add_co_u32_e32 v38, vcc, s18, v28
	s_cselect_b64 s[34:35], -1, 0
	s_nop 0
	v_addc_co_u32_e32 v39, vcc, 0, v29, vcc
	v_add_co_u32_e32 v40, vcc, s19, v28
	v_lshlrev_b32_e32 v1, 3, v1
	s_nop 0
	v_addc_co_u32_e32 v41, vcc, 0, v29, vcc
	v_add_co_u32_e32 v42, vcc, s28, v28
	v_cndmask_b32_e64 v3, 0, 1, s[34:35]
	s_cmp_lg_u64 s[34:35], 0
	v_and_b32_e32 v1, 0x78, v1
	v_addc_co_u32_e32 v43, vcc, 0, v29, vcc
	s_addc_u32 s34, s36, 0
	s_waitcnt vmcnt(3)
	v_lshlrev_b32_e32 v16, 1, v1
	v_mul_u32_u24_e32 v25, 0x104, v1
	v_lshl_add_u64 v[20:21], s[8:9], 0, v[6:7]
	s_lshl_b32 s8, s36, 6
	v_lshlrev_b32_e32 v1, 6, v3
	v_add_co_u32_e32 v44, vcc, s29, v28
	v_lshl_add_u64 v[4:5], s[10:11], 0, v[16:17]
	v_add_u32_e32 v1, s8, v1
	v_addc_co_u32_e32 v45, vcc, 0, v29, vcc
	v_lshl_add_u64 v[18:19], v[4:5], 0, s[6:7]
	v_mul_lo_u32 v24, v2, s30
	v_or_b32_e32 v26, v1, v22
	global_load_dword v7, v[36:37], off offset:-4096 nt
	global_load_dword v8, v[36:37], off nt
	global_load_dword v9, v[38:39], off offset:-4096 nt
	global_load_dword v10, v[38:39], off nt
	global_load_dword v11, v[40:41], off offset:-4096 nt
	global_load_dword v12, v[40:41], off nt
	global_load_dword v13, v[42:43], off offset:-4096 nt
	global_load_dword v16, v[42:43], off nt
	global_load_dword v2, v[28:29], off nt
	global_load_dword v1, v[30:31], off offset:-4096 nt
	global_load_dword v4, v[30:31], off nt
	global_load_dword v3, v[32:33], off offset:-4096 nt
	global_load_dword v6, v[32:33], off nt
	global_load_dword v5, v[34:35], off offset:-4096 nt
	global_load_dword v14, v[34:35], off nt
	global_load_dword v15, v[44:45], off nt
	s_lshl_b32 s35, s34, 6
	s_mov_b64 s[8:9], 0
	s_branch .LBB0_62

.LBB0_62:
	s_and_b64 s[10:11], s[8:9], exec
	s_cselect_b32 s10, 0x8200, 0
	s_add_i32 s36, s10, 0
	s_add_i32 s33, s34, s33
	s_cmp_gt_i32 s33, 1
	v_lshlrev_b32_e32 v27, 2, v22
	s_cselect_b64 s[10:11], -1, 0
	v_add3_u32 v27, s36, v27, v24
	s_and_b64 vcc, exec, s[10:11]
	s_waitcnt vmcnt(7)
	ds_write_b32 v27, v2
	s_waitcnt vmcnt(6)
	ds_write_b32 v27, v1 offset:2080
	s_waitcnt vmcnt(5)
	ds_write_b32 v27, v4 offset:4160
	s_waitcnt vmcnt(4)
	ds_write_b32 v27, v3 offset:6240
	s_waitcnt vmcnt(3)
	ds_write_b32 v27, v6 offset:8320
	s_waitcnt vmcnt(2)
	ds_write_b32 v27, v5 offset:10400
	s_waitcnt vmcnt(1)
	ds_write_b32 v27, v14 offset:12480
	ds_write_b32 v27, v7 offset:14560
	ds_write_b32 v27, v8 offset:16640
	ds_write_b32 v27, v9 offset:18720
	ds_write_b32 v27, v10 offset:20800
	ds_write_b32 v27, v11 offset:22880
	ds_write_b32 v27, v12 offset:24960
	ds_write_b32 v27, v13 offset:27040
	ds_write_b32 v27, v16 offset:29120
	s_waitcnt vmcnt(0)
	ds_write_b32 v27, v15 offset:31200
	s_cbranch_vccnz .LBB0_61
	v_add_u32_e32 v2, s4, v26
	v_ashrrev_i32_e32 v3, 31, v2
	v_lshl_add_u64 v[28:29], v[2:3], 2, v[20:21]
	v_add_co_u32_e32 v30, vcc, 0x1000, v28
	s_nop 1
	v_addc_co_u32_e32 v31, vcc, 0, v29, vcc
	v_add_co_u32_e32 v32, vcc, 0x2000, v28
	s_nop 1
	v_addc_co_u32_e32 v33, vcc, 0, v29, vcc
	v_add_co_u32_e32 v34, vcc, 0x3000, v28
	s_nop 1
	v_addc_co_u32_e32 v35, vcc, 0, v29, vcc
	v_add_co_u32_e32 v36, vcc, 0x4000, v28
	s_nop 1
	v_addc_co_u32_e32 v37, vcc, 0, v29, vcc
	v_add_co_u32_e32 v38, vcc, 0x5000, v28
	s_nop 1
	v_addc_co_u32_e32 v39, vcc, 0, v29, vcc
	v_add_co_u32_e32 v40, vcc, 0x6000, v28
	s_nop 1
	v_addc_co_u32_e32 v41, vcc, 0, v29, vcc
	v_add_co_u32_e32 v42, vcc, 0x7000, v28
	s_nop 1
	v_addc_co_u32_e32 v43, vcc, 0, v29, vcc
	v_add_co_u32_e32 v44, vcc, 0x8000, v28
	s_nop 1
	v_addc_co_u32_e32 v45, vcc, 0, v29, vcc
	v_add_co_u32_e32 v46, vcc, 0x9000, v28
	s_nop 1
	v_addc_co_u32_e32 v47, vcc, 0, v29, vcc
	v_add_co_u32_e32 v48, vcc, 0xa000, v28
	s_nop 1
	v_addc_co_u32_e32 v49, vcc, 0, v29, vcc
	v_add_co_u32_e32 v50, vcc, 0xb000, v28
	s_nop 1
	v_addc_co_u32_e32 v51, vcc, 0, v29, vcc
	v_add_co_u32_e32 v52, vcc, 0xc000, v28
	s_nop 1
	v_addc_co_u32_e32 v53, vcc, 0, v29, vcc
	v_add_co_u32_e32 v54, vcc, 0xd000, v28
	s_nop 1
	v_addc_co_u32_e32 v55, vcc, 0, v29, vcc
	v_add_co_u32_e32 v56, vcc, 0xe000, v28
	s_nop 1
	v_addc_co_u32_e32 v57, vcc, 0, v29, vcc
	v_add_co_u32_e32 v58, vcc, 0xf000, v28
	s_nop 1
	v_addc_co_u32_e32 v59, vcc, 0, v29, vcc
	global_load_dword v2, v[28:29], off nt
	global_load_dword v1, v[30:31], off nt
	global_load_dword v4, v[32:33], off nt
	global_load_dword v3, v[34:35], off nt
	global_load_dword v6, v[36:37], off nt
	global_load_dword v5, v[38:39], off nt
	global_load_dword v14, v[40:41], off nt
	global_load_dword v7, v[42:43], off nt
	global_load_dword v8, v[44:45], off nt
	global_load_dword v9, v[46:47], off nt
	global_load_dword v10, v[48:49], off nt
	global_load_dword v11, v[50:51], off nt
	global_load_dword v12, v[52:53], off nt
	global_load_dword v13, v[54:55], off nt
	global_load_dword v16, v[56:57], off nt
	global_load_dword v15, v[58:59], off nt
	s_branch .LBB0_61

.LBB0_66:
	s_waitcnt vmcnt(16)
	v_mov_b32_e32 v1, v208
	s_lshl_b32 s30, s29, 1
	s_sub_i32 s30, s2, s30
	s_sub_i32 s30, s30, 152
	s_cmp_gt_u32 s30, 1
	s_cbranch_scc1 .LBB0_65
	s_lshl_b32 s4, s29, 14
	s_lshl_b64 s[8:9], s[4:5], 2
	s_add_u32 s8, s24, s8
	s_addc_u32 s9, s25, s9
	s_lshl_b32 s4, s29, 15
	s_add_u32 s10, s12, s4
	v_and_b32_e32 v22, 63, v1
	s_addc_u32 s11, s13, 0
	s_lshl_b32 s4, s30, 6
	v_ashrrev_i32_e32 v2, 6, v1
	s_waitcnt vmcnt(15)
	v_or_b32_e32 v4, s4, v22
	s_waitcnt vmcnt(12)
	v_ashrrev_i32_e32 v5, 31, v4
	v_ashrrev_i32_e32 v3, 31, v2
	v_lshl_add_u64 v[4:5], v[4:5], 2, s[8:9]
	s_waitcnt vmcnt(10)
	v_lshlrev_b64 v[6:7], 9, v[2:3]
	v_lshl_add_u64 v[28:29], v[4:5], 0, v[6:7]
	v_add_co_u32_e32 v30, vcc, s14, v28
	s_load_dword s36, s[62:63], 0x0
	s_load_dword s31, s[62:63], 0x10
	v_addc_co_u32_e32 v31, vcc, 0, v29, vcc
	v_add_co_u32_e32 v32, vcc, s15, v28
	s_waitcnt lgkmcnt(0)
	s_lshr_b32 s31, s31, 16
	v_addc_co_u32_e32 v33, vcc, 0, v29, vcc
	v_add_co_u32_e32 v34, vcc, s16, v28
	s_cmp_lg_u32 s31, 0
	s_nop 0
	v_addc_co_u32_e32 v35, vcc, 0, v29, vcc
	v_add_co_u32_e32 v36, vcc, s17, v28
	v_ashrrev_i32_e32 v23, 4, v1
	s_nop 0
	v_addc_co_u32_e32 v37, vcc, 0, v29, vcc
	v_add_co_u32_e32 v38, vcc, s18, v28
	s_cselect_b64 s[34:35], -1, 0
	s_nop 0
	v_addc_co_u32_e32 v39, vcc, 0, v29, vcc
	v_add_co_u32_e32 v40, vcc, s19, v28
	v_lshlrev_b32_e32 v1, 3, v1
	s_nop 0
	v_addc_co_u32_e32 v41, vcc, 0, v29, vcc
	v_add_co_u32_e32 v42, vcc, s26, v28
	v_cndmask_b32_e64 v3, 0, 1, s[34:35]
	s_cmp_lg_u64 s[34:35], 0
	v_and_b32_e32 v1, 0x78, v1
	v_addc_co_u32_e32 v43, vcc, 0, v29, vcc
	s_addc_u32 s31, s36, 0
	s_waitcnt vmcnt(3)
	v_lshlrev_b32_e32 v16, 1, v1
	v_mul_u32_u24_e32 v25, 0x104, v1
	v_lshl_add_u64 v[20:21], s[8:9], 0, v[6:7]
	s_lshl_b32 s8, s36, 6
	v_lshlrev_b32_e32 v1, 6, v3
	v_add_co_u32_e32 v44, vcc, s27, v28
	v_lshl_add_u64 v[4:5], s[10:11], 0, v[16:17]
	v_add_u32_e32 v1, s8, v1
	v_addc_co_u32_e32 v45, vcc, 0, v29, vcc
	v_lshl_add_u64 v[18:19], v[4:5], 0, s[6:7]
	v_mul_lo_u32 v24, v2, s28
	v_or_b32_e32 v26, v1, v22
	global_load_dword v7, v[36:37], off offset:-4096 nt
	global_load_dword v8, v[36:37], off nt
	global_load_dword v9, v[38:39], off offset:-4096 nt
	global_load_dword v10, v[38:39], off nt
	global_load_dword v11, v[40:41], off offset:-4096 nt
	global_load_dword v12, v[40:41], off nt
	global_load_dword v13, v[42:43], off offset:-4096 nt
	global_load_dword v16, v[42:43], off nt
	global_load_dword v2, v[28:29], off nt
	global_load_dword v1, v[30:31], off offset:-4096 nt
	global_load_dword v4, v[30:31], off nt
	global_load_dword v3, v[32:33], off offset:-4096 nt
	global_load_dword v6, v[32:33], off nt
	global_load_dword v5, v[34:35], off offset:-4096 nt
	global_load_dword v14, v[34:35], off nt
	global_load_dword v15, v[44:45], off nt
	s_lshl_b32 s33, s31, 6
	s_mov_b64 s[8:9], 0
	s_branch .LBB0_69

.LBB0_69:
	s_and_b64 s[10:11], s[8:9], exec
	s_cselect_b32 s10, 0x8200, 0
	s_add_i32 s34, s10, 0
	s_add_i32 s30, s31, s30
	s_cmp_gt_i32 s30, 1
	v_lshlrev_b32_e32 v27, 2, v22
	s_cselect_b64 s[10:11], -1, 0
	v_add3_u32 v27, s34, v27, v24
	s_and_b64 vcc, exec, s[10:11]
	s_waitcnt vmcnt(7)
	ds_write_b32 v27, v2
	s_waitcnt vmcnt(6)
	ds_write_b32 v27, v1 offset:2080
	s_waitcnt vmcnt(5)
	ds_write_b32 v27, v4 offset:4160
	s_waitcnt vmcnt(4)
	ds_write_b32 v27, v3 offset:6240
	s_waitcnt vmcnt(3)
	ds_write_b32 v27, v6 offset:8320
	s_waitcnt vmcnt(2)
	ds_write_b32 v27, v5 offset:10400
	s_waitcnt vmcnt(1)
	ds_write_b32 v27, v14 offset:12480
	ds_write_b32 v27, v7 offset:14560
	ds_write_b32 v27, v8 offset:16640
	ds_write_b32 v27, v9 offset:18720
	ds_write_b32 v27, v10 offset:20800
	ds_write_b32 v27, v11 offset:22880
	ds_write_b32 v27, v12 offset:24960
	ds_write_b32 v27, v13 offset:27040
	ds_write_b32 v27, v16 offset:29120
	s_waitcnt vmcnt(0)
	ds_write_b32 v27, v15 offset:31200
	s_cbranch_vccnz .LBB0_68
	v_add_u32_e32 v2, s4, v26
	v_ashrrev_i32_e32 v3, 31, v2
	v_lshl_add_u64 v[28:29], v[2:3], 2, v[20:21]
	v_add_co_u32_e32 v30, vcc, 0x1000, v28
	s_nop 1
	v_addc_co_u32_e32 v31, vcc, 0, v29, vcc
	v_add_co_u32_e32 v32, vcc, 0x2000, v28
	s_nop 1
	v_addc_co_u32_e32 v33, vcc, 0, v29, vcc
	v_add_co_u32_e32 v34, vcc, 0x3000, v28
	s_nop 1
	v_addc_co_u32_e32 v35, vcc, 0, v29, vcc
	v_add_co_u32_e32 v36, vcc, 0x4000, v28
	s_nop 1
	v_addc_co_u32_e32 v37, vcc, 0, v29, vcc
	v_add_co_u32_e32 v38, vcc, 0x5000, v28
	s_nop 1
	v_addc_co_u32_e32 v39, vcc, 0, v29, vcc
	v_add_co_u32_e32 v40, vcc, 0x6000, v28
	s_nop 1
	v_addc_co_u32_e32 v41, vcc, 0, v29, vcc
	v_add_co_u32_e32 v42, vcc, 0x7000, v28
	s_nop 1
	v_addc_co_u32_e32 v43, vcc, 0, v29, vcc
	v_add_co_u32_e32 v44, vcc, 0x8000, v28
	s_nop 1
	v_addc_co_u32_e32 v45, vcc, 0, v29, vcc
	v_add_co_u32_e32 v46, vcc, 0x9000, v28
	s_nop 1
	v_addc_co_u32_e32 v47, vcc, 0, v29, vcc
	v_add_co_u32_e32 v48, vcc, 0xa000, v28
	s_nop 1
	v_addc_co_u32_e32 v49, vcc, 0, v29, vcc
	v_add_co_u32_e32 v50, vcc, 0xb000, v28
	s_nop 1
	v_addc_co_u32_e32 v51, vcc, 0, v29, vcc
	v_add_co_u32_e32 v52, vcc, 0xc000, v28
	s_nop 1
	v_addc_co_u32_e32 v53, vcc, 0, v29, vcc
	v_add_co_u32_e32 v54, vcc, 0xd000, v28
	s_nop 1
	v_addc_co_u32_e32 v55, vcc, 0, v29, vcc
	v_add_co_u32_e32 v56, vcc, 0xe000, v28
	s_nop 1
	v_addc_co_u32_e32 v57, vcc, 0, v29, vcc
	v_add_co_u32_e32 v58, vcc, 0xf000, v28
	s_nop 1
	v_addc_co_u32_e32 v59, vcc, 0, v29, vcc
	global_load_dword v2, v[28:29], off nt
	global_load_dword v1, v[30:31], off nt
	global_load_dword v4, v[32:33], off nt
	global_load_dword v3, v[34:35], off nt
	global_load_dword v6, v[36:37], off nt
	global_load_dword v5, v[38:39], off nt
	global_load_dword v14, v[40:41], off nt
	global_load_dword v7, v[42:43], off nt
	global_load_dword v8, v[44:45], off nt
	global_load_dword v9, v[46:47], off nt
	global_load_dword v10, v[48:49], off nt
	global_load_dword v11, v[50:51], off nt
	global_load_dword v12, v[52:53], off nt
	global_load_dword v13, v[54:55], off nt
	global_load_dword v16, v[56:57], off nt
	global_load_dword v15, v[58:59], off nt
	s_branch .LBB0_68

.Ldg0_b96:
	s_waitcnt vmcnt(17)
	v_mov_b32_e32 v0, v208
	s_mov_b32 s24, s2
	s_waitcnt lgkmcnt(0)
	s_barrier
	s_cmpk_gt_i32 s24, 0x7ff
	s_cbranch_scc1 .Ldc_g0_done
	s_add_u32 s42, s42, 0
	s_addc_u32 s43, s43, 0
	s_ashr_i32 s26, s24, 31
	s_lshr_b32 s26, s26, 28
	s_add_i32 s26, s24, s26
	s_ashr_i32 s27, s26, 4
	v_and_b32_e32 v20, 63, v0
	s_lshl_b32 s28, s27, 6
	s_waitcnt vmcnt(16)
	v_or_b32_e32 v1, s28, v20
	v_bfe_u32 v23, v0, 4, 1
	v_ashrrev_i32_e32 v26, 6, v0
	v_and_b32_e32 v21, 15, v0
	v_ashrrev_i32_e32 v22, 4, v0
	s_waitcnt vmcnt(15)
	v_and_or_b32 v2, s27, 2, v23
	s_ashr_i32 s27, s28, 2
	v_lshrrev_b32_e32 v0, 1, v1
	s_andn2_b32 s27, s27, 63
	v_and_b32_e32 v0, 48, v0
	s_and_b32 s26, s26, 0x1fffff0
	v_or3_b32 v0, s27, v0, v21
	s_waitcnt vmcnt(3)
	v_lshlrev_b32_e32 v16, 13, v2
	s_sub_i32 s26, s24, s26
	v_lshl_add_u64 v[2:3], s[42:43], 0, v[16:17]
	v_ashrrev_i32_e32 v1, 31, v0
	v_lshl_add_u64 v[0:1], v[0:1], 2, v[2:3]
	v_lshl_add_u32 v2, s26, 7, v26
	v_ashrrev_i32_e32 v3, 31, v2
	v_lshlrev_b64 v[2:3], 15, v[2:3]
	v_lshl_add_u64 v[0:1], v[0:1], 0, v[2:3]
	v_add_co_u32_e32 v2, vcc, s20, v0
	s_mov_b32 s26, 0x100000
	s_nop 0
	v_addc_co_u32_e32 v3, vcc, 0, v1, vcc
	v_add_co_u32_e32 v4, vcc, s64, v0
	v_lshlrev_b32_e32 v16, 4, v21
	s_nop 0
	v_addc_co_u32_e32 v5, vcc, 0, v1, vcc
	v_add_co_u32_e32 v6, vcc, s66, v0
	v_lshl_add_u64 v[18:19], s[18:19], 0, v[16:17]
	s_nop 0
	v_addc_co_u32_e32 v7, vcc, 0, v1, vcc
	v_add_co_u32_e32 v8, vcc, s26, v0
	s_mov_b32 s26, 0x140000
	s_nop 0
	v_addc_co_u32_e32 v9, vcc, 0, v1, vcc
	v_add_co_u32_e32 v10, vcc, s26, v0
	s_mov_b32 s26, 0x180000
	s_nop 0
	v_addc_co_u32_e32 v11, vcc, 0, v1, vcc
	v_add_co_u32_e32 v12, vcc, s26, v0
	s_mov_b32 s26, 0x1c0000
	s_nop 0
	v_addc_co_u32_e32 v13, vcc, 0, v1, vcc
	v_add_co_u32_e32 v14, vcc, s26, v0
	s_mov_b32 s26, 0x200000
	s_waitcnt vmcnt(2)
	v_addc_co_u32_e32 v15, vcc, 0, v1, vcc
	v_add_co_u32_e32 v28, vcc, s26, v0
	s_mov_b32 s26, 0x240000
	s_nop 0
	v_addc_co_u32_e32 v29, vcc, 0, v1, vcc
	v_add_co_u32_e32 v30, vcc, s26, v0
	s_mov_b32 s26, 0x280000
	s_nop 0
	v_addc_co_u32_e32 v31, vcc, 0, v1, vcc
	v_add_co_u32_e32 v32, vcc, s26, v0
	s_mov_b32 s26, 0x2c0000
	s_nop 0
	v_addc_co_u32_e32 v33, vcc, 0, v1, vcc
	v_add_co_u32_e32 v34, vcc, s26, v0
	s_mov_b32 s26, 0x300000
	s_nop 0
	v_addc_co_u32_e32 v35, vcc, 0, v1, vcc
	v_add_co_u32_e32 v36, vcc, s26, v0
	s_mov_b32 s26, 0x340000
	s_nop 0
	v_addc_co_u32_e32 v37, vcc, 0, v1, vcc
	v_add_co_u32_e32 v38, vcc, s26, v0
	s_mov_b32 s26, 0x380000
	s_nop 0
	v_addc_co_u32_e32 v39, vcc, 0, v1, vcc
	v_add_co_u32_e32 v40, vcc, s26, v0
	s_mov_b32 s26, 0x3c0000
	s_nop 0
	v_addc_co_u32_e32 v41, vcc, 0, v1, vcc
	v_add_co_u32_e32 v42, vcc, s26, v0
	s_mov_b64 s[26:27], 0x1378000
	s_nop 0
	v_addc_co_u32_e32 v43, vcc, 0, v1, vcc
	global_load_dword v0, v[0:1], off nt
	s_nop 0
	global_load_dword v1, v[2:3], off nt
	s_nop 0
	global_load_dword v2, v[4:5], off nt
	global_load_dword v3, v[6:7], off nt
	s_nop 0
	global_load_dword v4, v[8:9], off nt
	global_load_dword v5, v[10:11], off nt
	global_load_dword v6, v[12:13], off nt
	global_load_dword v7, v[14:15], off nt
	s_nop 0
	global_load_dword v8, v[28:29], off nt
	global_load_dword v9, v[30:31], off nt
	global_load_dword v10, v[32:33], off nt
	global_load_dword v11, v[34:35], off nt
	global_load_dword v12, v[36:37], off nt
	global_load_dword v13, v[38:39], off nt
	global_load_dword v14, v[40:41], off nt
	global_load_dword v15, v[42:43], off nt
	v_lshl_add_u64 v[18:19], v[18:19], 0, s[26:27]
	s_movk_i32 s26, 0x104
	s_lshl_b32 s27, s60, 7
	v_mul_lo_u32 v24, v26, s26
	v_mul_u32_u24_e32 v25, 0x820, v21
	s_lshl_b32 s26, s24, 7
	v_add_u32_e32 v26, s27, v26
	s_mov_b64 s[48:49], 0
	s_branch .Ldg0_b99

.Ldg0_b99:
	s_and_b64 s[28:29], s[48:49], exec
	s_cselect_b32 s28, 0x8200, 0
	s_add_i32 s37, s28, 0
	s_add_i32 s36, s24, s60
	s_cmpk_gt_i32 s36, 0x7ff
	v_lshlrev_b32_e32 v16, 2, v20
	s_cselect_b64 s[28:29], -1, 0
	v_add3_u32 v16, s37, v16, v24
	s_and_b64 vcc, exec, s[28:29]
	s_waitcnt vmcnt(15)
	ds_write_b32 v16, v0
	s_waitcnt vmcnt(14)
	ds_write_b32 v16, v1 offset:2080
	s_waitcnt vmcnt(13)
	ds_write_b32 v16, v2 offset:4160
	s_waitcnt vmcnt(12)
	ds_write_b32 v16, v3 offset:6240
	s_waitcnt vmcnt(11)
	ds_write_b32 v16, v4 offset:8320
	s_waitcnt vmcnt(10)
	ds_write_b32 v16, v5 offset:10400
	s_waitcnt vmcnt(9)
	ds_write_b32 v16, v6 offset:12480
	s_waitcnt vmcnt(8)
	ds_write_b32 v16, v7 offset:14560
	s_waitcnt vmcnt(7)
	ds_write_b32 v16, v8 offset:16640
	s_waitcnt vmcnt(6)
	ds_write_b32 v16, v9 offset:18720
	s_waitcnt vmcnt(5)
	ds_write_b32 v16, v10 offset:20800
	s_waitcnt vmcnt(4)
	ds_write_b32 v16, v11 offset:22880
	s_waitcnt vmcnt(3)
	ds_write_b32 v16, v12 offset:24960
	s_waitcnt vmcnt(2)
	ds_write_b32 v16, v13 offset:27040
	s_waitcnt vmcnt(1)
	ds_write_b32 v16, v14 offset:29120
	s_waitcnt vmcnt(0)
	ds_write_b32 v16, v15 offset:31200
	s_cbranch_vccnz .Ldg0_b98
	s_ashr_i32 s52, s36, 31
	s_lshr_b32 s52, s52, 28
	s_add_i32 s52, s36, s52
	s_ashr_i32 s52, s52, 4
	s_lshl_b32 s53, s52, 6
	v_or_b32_e32 v0, s53, v20
	s_ashr_i32 s53, s53, 2
	v_lshrrev_b32_e32 v0, 1, v0
	v_and_or_b32 v1, s52, 2, v23
	s_andn2_b32 s53, s53, 63
	v_and_b32_e32 v0, 48, v0
	v_or3_b32 v0, s53, v0, v21
	v_lshlrev_b32_e32 v16, 13, v1
	v_lshl_add_u64 v[2:3], s[42:43], 0, v[16:17]
	v_ashrrev_i32_e32 v1, 31, v0
	v_lshl_add_u64 v[0:1], v[0:1], 2, v[2:3]
	v_add_u32_e32 v2, s26, v26
	s_lshl_b32 s52, s52, 11
	v_subrev_u32_e32 v2, s52, v2
	v_ashrrev_i32_e32 v3, 31, v2
	v_lshlrev_b64 v[2:3], 15, v[2:3]
	v_lshl_add_u64 v[0:1], v[0:1], 0, v[2:3]
	v_add_co_u32_e32 v2, vcc, s20, v0
	s_mov_b32 s52, 0x100000
	s_nop 0
	v_addc_co_u32_e32 v3, vcc, 0, v1, vcc
	v_add_co_u32_e32 v4, vcc, s64, v0
	s_nop 1
	v_addc_co_u32_e32 v5, vcc, 0, v1, vcc
	v_add_co_u32_e32 v6, vcc, s66, v0
	s_nop 1
	v_addc_co_u32_e32 v7, vcc, 0, v1, vcc
	v_add_co_u32_e32 v8, vcc, s52, v0
	s_mov_b32 s52, 0x140000
	s_nop 0
	v_addc_co_u32_e32 v9, vcc, 0, v1, vcc
	v_add_co_u32_e32 v10, vcc, s52, v0
	s_mov_b32 s52, 0x180000
	s_nop 0
	v_addc_co_u32_e32 v11, vcc, 0, v1, vcc
	v_add_co_u32_e32 v12, vcc, s52, v0
	s_mov_b32 s52, 0x1c0000
	s_nop 0
	v_addc_co_u32_e32 v13, vcc, 0, v1, vcc
	v_add_co_u32_e32 v14, vcc, s52, v0
	s_mov_b32 s52, 0x200000
	s_nop 0
	v_addc_co_u32_e32 v15, vcc, 0, v1, vcc
	v_add_co_u32_e32 v28, vcc, s52, v0
	s_mov_b32 s52, 0x240000
	s_nop 0
	v_addc_co_u32_e32 v29, vcc, 0, v1, vcc
	v_add_co_u32_e32 v30, vcc, s52, v0
	s_mov_b32 s52, 0x280000
	s_nop 0
	v_addc_co_u32_e32 v31, vcc, 0, v1, vcc
	v_add_co_u32_e32 v32, vcc, s52, v0
	s_mov_b32 s52, 0x2c0000
	s_nop 0
	v_addc_co_u32_e32 v33, vcc, 0, v1, vcc
	v_add_co_u32_e32 v34, vcc, s52, v0
	s_mov_b32 s52, 0x300000
	s_nop 0
	v_addc_co_u32_e32 v35, vcc, 0, v1, vcc
	v_add_co_u32_e32 v36, vcc, s52, v0
	s_nop 1
	v_addc_co_u32_e32 v37, vcc, 0, v1, vcc
	v_add_co_u32_e32 v38, vcc, 0x340000, v0
	s_nop 1
	v_addc_co_u32_e32 v39, vcc, 0, v1, vcc
	v_add_co_u32_e32 v40, vcc, 0x380000, v0
	s_nop 1
	v_addc_co_u32_e32 v41, vcc, 0, v1, vcc
	v_add_co_u32_e32 v42, vcc, 0x3c0000, v0
	s_nop 1
	v_addc_co_u32_e32 v43, vcc, 0, v1, vcc
	global_load_dword v0, v[0:1], off nt
	s_nop 0
	global_load_dword v1, v[2:3], off nt
	s_nop 0
	global_load_dword v2, v[4:5], off nt
	global_load_dword v3, v[6:7], off nt
	s_nop 0
	global_load_dword v4, v[8:9], off nt
	global_load_dword v5, v[10:11], off nt
	global_load_dword v6, v[12:13], off nt
	global_load_dword v7, v[14:15], off nt
	s_nop 0
	global_load_dword v8, v[28:29], off nt
	global_load_dword v9, v[30:31], off nt
	global_load_dword v10, v[32:33], off nt
	global_load_dword v11, v[34:35], off nt
	global_load_dword v12, v[36:37], off nt
	global_load_dword v13, v[38:39], off nt
	global_load_dword v14, v[40:41], off nt
	global_load_dword v15, v[42:43], off nt
	s_branch .Ldg0_b98

.Ldw1_b118:
	s_waitcnt vmcnt(17)
	v_mov_b32_e32 v0, v208
	s_mov_b32 s24, s2
	s_barrier
	s_cmpk_gt_i32 s24, 0x57f
	s_cbranch_scc1 .Ldc_w1_done
	s_add_u32 s40, s58, 0x2c00000
	s_mul_hi_i32 s26, s24, 0x2e8ba2e9
	s_addc_u32 s41, s59, 0
	s_lshr_b32 s27, s26, 31
	s_ashr_i32 s26, s26, 3
	s_add_i32 s26, s26, s27
	s_mul_i32 s27, s26, 44
	v_and_b32_e32 v20, 63, v0
	v_ashrrev_i32_e32 v23, 6, v0
	s_sub_i32 s27, s24, s27
	s_waitcnt vmcnt(15)
	v_lshl_or_b32 v2, s26, 6, v20
	s_waitcnt vmcnt(13)
	v_lshl_add_u32 v4, s27, 7, v23
	v_ashrrev_i32_e32 v3, 31, v2
	s_waitcnt vmcnt(12)
	v_ashrrev_i32_e32 v5, 31, v4
	v_lshl_add_u64 v[2:3], v[2:3], 2, s[40:41]
	v_lshlrev_b64 v[4:5], 13, v[4:5]
	v_lshl_add_u64 v[2:3], v[2:3], 0, v[4:5]
	v_add_co_u32_e32 v4, vcc, s67, v2
	s_mov_b32 s26, 0xb0000
	s_nop 0
	v_addc_co_u32_e32 v5, vcc, 0, v3, vcc
	s_waitcnt vmcnt(11)
	v_add_co_u32_e32 v6, vcc, s17, v2
	v_ashrrev_i32_e32 v21, 4, v0
	s_waitcnt vmcnt(10)
	v_addc_co_u32_e32 v7, vcc, 0, v3, vcc
	s_waitcnt vmcnt(9)
	v_add_co_u32_e32 v8, vcc, s74, v2
	s_mov_b32 s27, 0xf0000
	s_waitcnt vmcnt(8)
	v_addc_co_u32_e32 v9, vcc, 0, v3, vcc
	s_waitcnt vmcnt(7)
	v_add_co_u32_e32 v10, vcc, s20, v2
	v_lshlrev_b32_e32 v0, 3, v0
	s_waitcnt vmcnt(6)
	v_addc_co_u32_e32 v11, vcc, 0, v3, vcc
	s_waitcnt vmcnt(5)
	v_add_co_u32_e32 v12, vcc, s75, v2
	v_and_b32_e32 v22, 0x78, v0
	s_waitcnt vmcnt(4)
	v_addc_co_u32_e32 v13, vcc, 0, v3, vcc
	s_waitcnt vmcnt(3)
	v_add_co_u32_e32 v14, vcc, s21, v2
	v_lshlrev_b32_e32 v16, 1, v22
	s_waitcnt vmcnt(2)
	v_addc_co_u32_e32 v15, vcc, 0, v3, vcc
	v_add_co_u32_e32 v24, vcc, s30, v2
	v_lshl_add_u64 v[0:1], s[18:19], 0, v[16:17]
	s_nop 0
	v_addc_co_u32_e32 v25, vcc, 0, v3, vcc
	v_add_co_u32_e32 v26, vcc, s64, v2
	v_mul_u32_u24_e32 v22, 0x104, v22
	s_nop 0
	v_addc_co_u32_e32 v27, vcc, 0, v3, vcc
	v_add_co_u32_e32 v28, vcc, s31, v2
	s_mov_b64 s[42:43], 0
	s_nop 0
	v_addc_co_u32_e32 v29, vcc, 0, v3, vcc
	v_add_co_u32_e32 v30, vcc, s65, v2
	s_nop 1
	v_addc_co_u32_e32 v31, vcc, 0, v3, vcc
	v_add_co_u32_e32 v32, vcc, s26, v2
	s_mov_b32 s26, 0xd0000
	s_nop 0
	v_addc_co_u32_e32 v33, vcc, 0, v3, vcc
	v_add_co_u32_e32 v34, vcc, s66, v2
	s_nop 1
	v_addc_co_u32_e32 v35, vcc, 0, v3, vcc
	v_add_co_u32_e32 v36, vcc, s26, v2
	s_mov_b32 s26, 0xe0000
	s_nop 0
	v_addc_co_u32_e32 v37, vcc, 0, v3, vcc
	v_add_co_u32_e32 v38, vcc, s26, v2
	s_load_dword s28, s[62:63], 0x0
	s_load_dword s26, s[62:63], 0x10
	v_addc_co_u32_e32 v39, vcc, 0, v3, vcc
	v_add_co_u32_e32 v40, vcc, s27, v2
	s_waitcnt lgkmcnt(0)
	s_lshr_b32 s26, s26, 16
	s_cmp_lg_u32 s26, 0
	s_cselect_b64 s[26:27], -1, 0
	s_cmp_lg_u64 s[26:27], 0
	s_addc_u32 s26, s28, 0
	s_mov_b32 s26, s60
	s_mov_b64 s[28:29], 0x6f78000
	v_addc_co_u32_e32 v41, vcc, 0, v3, vcc
	v_lshl_add_u64 v[18:19], v[0:1], 0, s[28:29]
	global_load_dword v0, v[2:3], off nt
	global_load_dword v1, v[4:5], off nt
	s_nop 0
	global_load_dword v2, v[6:7], off nt
	global_load_dword v3, v[8:9], off nt
	global_load_dword v4, v[10:11], off nt
	global_load_dword v5, v[12:13], off nt
	s_nop 0
	global_load_dword v6, v[14:15], off nt
	global_load_dword v7, v[24:25], off nt
	global_load_dword v8, v[26:27], off nt
	global_load_dword v9, v[28:29], off nt
	global_load_dword v10, v[30:31], off nt
	global_load_dword v11, v[32:33], off nt
	global_load_dword v12, v[34:35], off nt
	global_load_dword v13, v[36:37], off nt
	global_load_dword v14, v[38:39], off nt
	global_load_dword v15, v[40:41], off nt
	s_movk_i32 s27, 0x104
	s_lshl_b32 s36, s26, 7
	v_mul_lo_u32 v16, v23, s27
	s_lshl_b32 s27, s24, 7
	v_add_u32_e32 v23, s36, v23
	s_branch .Ldw1_b121

.Ldw1_b121:
	s_and_b64 s[28:29], s[42:43], exec
	s_cselect_b32 s28, 0x8200, 0
	s_add_i32 s44, s28, 0
	s_add_i32 s37, s26, s24
	s_cmpk_gt_i32 s37, 0x57f
	v_lshlrev_b32_e32 v24, 2, v20
	s_cselect_b64 s[28:29], -1, 0
	v_add3_u32 v24, s44, v24, v16
	s_and_b64 vcc, exec, s[28:29]
	s_waitcnt vmcnt(15)
	ds_write_b32 v24, v0
	s_waitcnt vmcnt(14)
	ds_write_b32 v24, v1 offset:2080
	s_waitcnt vmcnt(13)
	ds_write_b32 v24, v2 offset:4160
	s_waitcnt vmcnt(12)
	ds_write_b32 v24, v3 offset:6240
	s_waitcnt vmcnt(11)
	ds_write_b32 v24, v4 offset:8320
	s_waitcnt vmcnt(10)
	ds_write_b32 v24, v5 offset:10400
	s_waitcnt vmcnt(9)
	ds_write_b32 v24, v6 offset:12480
	s_waitcnt vmcnt(8)
	ds_write_b32 v24, v7 offset:14560
	s_waitcnt vmcnt(7)
	ds_write_b32 v24, v8 offset:16640
	s_waitcnt vmcnt(6)
	ds_write_b32 v24, v9 offset:18720
	s_waitcnt vmcnt(5)
	ds_write_b32 v24, v10 offset:20800
	s_waitcnt vmcnt(4)
	ds_write_b32 v24, v11 offset:22880
	s_waitcnt vmcnt(3)
	ds_write_b32 v24, v12 offset:24960
	s_waitcnt vmcnt(2)
	ds_write_b32 v24, v13 offset:27040
	s_waitcnt vmcnt(1)
	ds_write_b32 v24, v14 offset:29120
	s_waitcnt vmcnt(0)
	ds_write_b32 v24, v15 offset:31200
	s_cbranch_vccnz .Ldw1_b120
	s_mul_hi_i32 s45, s37, 0x2e8ba2e9
	s_lshr_b32 s46, s45, 31
	s_ashr_i32 s45, s45, 3
	s_add_i32 s45, s45, s46
	v_lshl_or_b32 v0, s45, 6, v20
	s_mulk_i32 s45, 0xea00
	s_add_i32 s45, s45, s27
	v_add_u32_e32 v2, s45, v23
	v_ashrrev_i32_e32 v1, 31, v0
	v_ashrrev_i32_e32 v3, 31, v2
	v_lshl_add_u64 v[0:1], v[0:1], 2, s[40:41]
	v_lshlrev_b64 v[2:3], 13, v[2:3]
	v_lshl_add_u64 v[0:1], v[0:1], 0, v[2:3]
	v_add_co_u32_e32 v2, vcc, s67, v0
	s_nop 1
	v_addc_co_u32_e32 v3, vcc, 0, v1, vcc
	v_add_co_u32_e32 v4, vcc, s17, v0
	s_nop 1
	v_addc_co_u32_e32 v5, vcc, 0, v1, vcc
	v_add_co_u32_e32 v6, vcc, s74, v0
	s_nop 1
	v_addc_co_u32_e32 v7, vcc, 0, v1, vcc
	v_add_co_u32_e32 v8, vcc, s20, v0
	s_nop 1
	v_addc_co_u32_e32 v9, vcc, 0, v1, vcc
	v_add_co_u32_e32 v10, vcc, s75, v0
	s_nop 1
	v_addc_co_u32_e32 v11, vcc, 0, v1, vcc
	v_add_co_u32_e32 v12, vcc, s21, v0
	s_nop 1
	v_addc_co_u32_e32 v13, vcc, 0, v1, vcc
	v_add_co_u32_e32 v14, vcc, s30, v0
	s_nop 1
	v_addc_co_u32_e32 v15, vcc, 0, v1, vcc
	v_add_co_u32_e32 v24, vcc, s64, v0
	s_nop 1
	v_addc_co_u32_e32 v25, vcc, 0, v1, vcc
	v_add_co_u32_e32 v26, vcc, s31, v0
	s_nop 1
	v_addc_co_u32_e32 v27, vcc, 0, v1, vcc
	v_add_co_u32_e32 v28, vcc, s65, v0
	s_nop 1
	v_addc_co_u32_e32 v29, vcc, 0, v1, vcc
	v_add_co_u32_e32 v30, vcc, 0xb0000, v0
	s_nop 1
	v_addc_co_u32_e32 v31, vcc, 0, v1, vcc
	v_add_co_u32_e32 v32, vcc, s66, v0
	s_nop 1
	v_addc_co_u32_e32 v33, vcc, 0, v1, vcc
	v_add_co_u32_e32 v34, vcc, 0xd0000, v0
	s_nop 1
	v_addc_co_u32_e32 v35, vcc, 0, v1, vcc
	v_add_co_u32_e32 v36, vcc, 0xe0000, v0
	s_nop 1
	v_addc_co_u32_e32 v37, vcc, 0, v1, vcc
	v_add_co_u32_e32 v38, vcc, 0xf0000, v0
	s_nop 1
	v_addc_co_u32_e32 v39, vcc, 0, v1, vcc
	global_load_dword v0, v[0:1], off nt
	s_nop 0
	global_load_dword v1, v[2:3], off nt
	s_nop 0
	global_load_dword v2, v[4:5], off nt
	global_load_dword v3, v[6:7], off nt
	s_nop 0
	global_load_dword v4, v[8:9], off nt
	global_load_dword v5, v[10:11], off nt
	global_load_dword v6, v[12:13], off nt
	global_load_dword v7, v[14:15], off nt
	s_nop 0
	global_load_dword v8, v[24:25], off nt
	global_load_dword v9, v[26:27], off nt
	global_load_dword v10, v[28:29], off nt
	global_load_dword v11, v[30:31], off nt
	global_load_dword v12, v[32:33], off nt
	global_load_dword v13, v[34:35], off nt
	global_load_dword v14, v[36:37], off nt
	global_load_dword v15, v[38:39], off nt
	s_branch .Ldw1_b120

.Ldu0_b113:
	s_waitcnt vmcnt(17)
	v_mov_b32_e32 v0, v208
	s_mov_b32 s37, s2
	s_barrier
	s_cmpk_gt_i32 s37, 0xaff
	s_cbranch_scc1 .Ldc_u0_done
	s_add_u32 s24, s46, 0
	s_addc_u32 s26, s47, 0
	s_add_u32 s27, s56, 0
	s_addc_u32 s36, s57, 0
	s_ashr_i32 s28, s37, 31
	s_lshr_b32 s28, s28, 28
	s_add_i32 s28, s37, s28
	s_ashr_i32 s29, s28, 4
	s_and_b32 s28, s28, 0x1fffff0
	s_lshl_b32 s40, s29, 6
	s_sub_i32 s41, s37, s28
	s_bitcmp0_b32 s29, 1
	s_cselect_b32 s42, s26, s36
	s_cselect_b32 s43, s24, s27
	s_ashr_i32 s28, s40, 1
	s_and_b32 s28, s28, 0xffffff80
	s_ashr_i32 s29, s28, 31
	v_and_b32_e32 v20, 63, v0
	s_lshl_b64 s[28:29], s[28:29], 2
	s_add_u32 s28, s43, s28
	s_waitcnt vmcnt(16)
	v_and_or_b32 v1, s40, 64, v20
	v_ashrrev_i32_e32 v24, 6, v0
	s_addc_u32 s29, s42, s29
	s_waitcnt vmcnt(3)
	v_lshlrev_b32_e32 v16, 2, v1
	v_lshl_add_u64 v[2:3], s[28:29], 0, v[16:17]
	v_lshl_add_u32 v1, s41, 7, v24
	s_movk_i32 s28, 0x5800
	v_mad_i64_i32 v[2:3], s[28:29], v1, s28, v[2:3]
	s_mov_b32 s28, 0x2c000
	s_nop 0
	v_add_co_u32_e32 v4, vcc, s28, v2
	s_mov_b32 s28, 0x58000
	s_nop 0
	v_addc_co_u32_e32 v5, vcc, 0, v3, vcc
	v_add_co_u32_e32 v6, vcc, s28, v2
	s_mov_b32 s28, 0x84000
	s_nop 0
	v_addc_co_u32_e32 v7, vcc, 0, v3, vcc
	v_add_co_u32_e32 v8, vcc, s28, v2
	s_mov_b32 s28, 0xb0000
	s_nop 0
	v_addc_co_u32_e32 v9, vcc, 0, v3, vcc
	v_add_co_u32_e32 v10, vcc, s28, v2
	s_mov_b32 s28, 0xdc000
	s_nop 0
	v_addc_co_u32_e32 v11, vcc, 0, v3, vcc
	v_add_co_u32_e32 v12, vcc, s28, v2
	s_mov_b32 s28, 0x108000
	s_nop 0
	v_addc_co_u32_e32 v13, vcc, 0, v3, vcc
	v_add_co_u32_e32 v14, vcc, s28, v2
	s_mov_b32 s28, 0x134000
	s_waitcnt vmcnt(2)
	v_addc_co_u32_e32 v15, vcc, 0, v3, vcc
	v_add_co_u32_e32 v26, vcc, s28, v2
	s_mov_b32 s28, 0x160000
	s_nop 0
	v_addc_co_u32_e32 v27, vcc, 0, v3, vcc
	v_add_co_u32_e32 v28, vcc, s28, v2
	s_mov_b32 s28, 0x18c000
	s_nop 0
	v_addc_co_u32_e32 v29, vcc, 0, v3, vcc
	v_add_co_u32_e32 v30, vcc, s28, v2
	s_mov_b32 s28, 0x1b8000
	s_nop 0
	v_addc_co_u32_e32 v31, vcc, 0, v3, vcc
	v_add_co_u32_e32 v32, vcc, s28, v2
	s_mov_b32 s28, 0x1e4000
	s_nop 0
	v_addc_co_u32_e32 v33, vcc, 0, v3, vcc
	v_add_co_u32_e32 v34, vcc, s28, v2
	s_mov_b32 s28, 0x210000
	s_nop 0
	v_addc_co_u32_e32 v35, vcc, 0, v3, vcc
	v_add_co_u32_e32 v36, vcc, s28, v2
	s_mov_b32 s28, 0x23c000
	s_nop 0
	v_addc_co_u32_e32 v37, vcc, 0, v3, vcc
	v_add_co_u32_e32 v38, vcc, s28, v2
	s_mov_b32 s28, 0x268000
	s_nop 0
	v_addc_co_u32_e32 v39, vcc, 0, v3, vcc
	v_add_co_u32_e32 v40, vcc, s28, v2
	s_load_dword s40, s[62:63], 0x0
	s_load_dword s28, s[62:63], 0x10
	v_ashrrev_i32_e32 v21, 4, v0
	v_lshlrev_b32_e32 v0, 3, v0
	v_addc_co_u32_e32 v41, vcc, 0, v3, vcc
	s_waitcnt lgkmcnt(0)
	s_lshr_b32 s28, s28, 16
	s_mov_b32 s29, 0x294000
	s_cmp_lg_u32 s28, 0
	v_and_b32_e32 v23, 0x78, v0
	v_add_co_u32_e32 v42, vcc, s29, v2
	s_cselect_b64 s[28:29], -1, 0
	v_lshlrev_b32_e32 v16, 1, v23
	s_cmp_lg_u64 s[28:29], 0
	v_lshl_add_u64 v[0:1], s[18:19], 0, v[16:17]
	s_mov_b64 s[28:29], 0x4378000
	v_addc_co_u32_e32 v43, vcc, 0, v3, vcc
	v_lshl_add_u64 v[18:19], v[0:1], 0, s[28:29]
	global_load_dword v0, v[2:3], off nt
	global_load_dword v1, v[4:5], off nt
	s_nop 0
	global_load_dword v2, v[6:7], off nt
	global_load_dword v3, v[8:9], off nt
	global_load_dword v4, v[10:11], off nt
	global_load_dword v5, v[12:13], off nt
	s_nop 0
	global_load_dword v6, v[14:15], off nt
	global_load_dword v7, v[26:27], off nt
	global_load_dword v8, v[28:29], off nt
	global_load_dword v9, v[30:31], off nt
	global_load_dword v10, v[32:33], off nt
	global_load_dword v11, v[34:35], off nt
	global_load_dword v12, v[36:37], off nt
	global_load_dword v13, v[38:39], off nt
	global_load_dword v14, v[40:41], off nt
	global_load_dword v15, v[42:43], off nt
	s_addc_u32 s42, s40, 0
	s_mov_b32 s42, s60
	s_movk_i32 s28, 0x104
	s_lshl_b32 s44, s42, 7
	v_mul_lo_u32 v22, v24, s28
	v_mul_u32_u24_e32 v23, 0x104, v23
	s_lshl_b32 s43, s37, 7
	v_add_u32_e32 v24, s44, v24
	s_mov_b64 s[40:41], 0
	s_branch .Ldu0_b116

.Ldu0_b116:
	s_and_b64 s[28:29], s[40:41], exec
	s_cselect_b32 s28, 0x8200, 0
	s_add_i32 s46, s28, 0
	s_add_i32 s45, s42, s37
	s_cmpk_gt_i32 s45, 0xaff
	v_lshlrev_b32_e32 v16, 2, v20
	s_cselect_b64 s[28:29], -1, 0
	v_add3_u32 v16, s46, v16, v22
	s_and_b64 vcc, exec, s[28:29]
	s_waitcnt vmcnt(15)
	ds_write_b32 v16, v0
	s_waitcnt vmcnt(14)
	ds_write_b32 v16, v1 offset:2080
	s_waitcnt vmcnt(13)
	ds_write_b32 v16, v2 offset:4160
	s_waitcnt vmcnt(12)
	ds_write_b32 v16, v3 offset:6240
	s_waitcnt vmcnt(11)
	ds_write_b32 v16, v4 offset:8320
	s_waitcnt vmcnt(10)
	ds_write_b32 v16, v5 offset:10400
	s_waitcnt vmcnt(9)
	ds_write_b32 v16, v6 offset:12480
	s_waitcnt vmcnt(8)
	ds_write_b32 v16, v7 offset:14560
	s_waitcnt vmcnt(7)
	ds_write_b32 v16, v8 offset:16640
	s_waitcnt vmcnt(6)
	ds_write_b32 v16, v9 offset:18720
	s_waitcnt vmcnt(5)
	ds_write_b32 v16, v10 offset:20800
	s_waitcnt vmcnt(4)
	ds_write_b32 v16, v11 offset:22880
	s_waitcnt vmcnt(3)
	ds_write_b32 v16, v12 offset:24960
	s_waitcnt vmcnt(2)
	ds_write_b32 v16, v13 offset:27040
	s_waitcnt vmcnt(1)
	ds_write_b32 v16, v14 offset:29120
	s_waitcnt vmcnt(0)
	ds_write_b32 v16, v15 offset:31200
	s_cbranch_vccnz .Ldu0_b115
	s_ashr_i32 s47, s45, 31
	s_lshr_b32 s47, s47, 28
	s_add_i32 s47, s45, s47
	s_ashr_i32 s47, s47, 4
	s_lshl_b32 s52, s47, 6
	s_bitcmp0_b32 s47, 1
	s_cselect_b32 s53, s26, s36
	s_cselect_b32 s56, s24, s27
	s_ashr_i32 s48, s52, 1
	s_and_b32 s48, s48, 0xffffff80
	s_ashr_i32 s49, s48, 31
	s_lshl_b64 s[48:49], s[48:49], 2
	s_add_u32 s48, s56, s48
	v_and_or_b32 v0, s52, 64, v20
	s_addc_u32 s49, s53, s49
	v_lshlrev_b32_e32 v16, 2, v0
	v_add_u32_e32 v2, s43, v24
	s_lshl_b32 s47, s47, 11
	v_lshl_add_u64 v[0:1], s[48:49], 0, v[16:17]
	v_subrev_u32_e32 v2, s47, v2
	s_movk_i32 s47, 0x5800
	v_mad_i64_i32 v[0:1], s[48:49], v2, s47, v[0:1]
	s_mov_b32 s47, 0x2c000
	v_add_co_u32_e32 v2, vcc, s47, v0
	s_mov_b32 s47, 0x58000
	s_nop 0
	v_addc_co_u32_e32 v3, vcc, 0, v1, vcc
	v_add_co_u32_e32 v4, vcc, s47, v0
	s_mov_b32 s47, 0x84000
	s_nop 0
	v_addc_co_u32_e32 v5, vcc, 0, v1, vcc
	v_add_co_u32_e32 v6, vcc, s47, v0
	s_mov_b32 s47, 0xb0000
	s_nop 0
	v_addc_co_u32_e32 v7, vcc, 0, v1, vcc
	v_add_co_u32_e32 v8, vcc, s47, v0
	s_mov_b32 s47, 0xdc000
	s_nop 0
	v_addc_co_u32_e32 v9, vcc, 0, v1, vcc
	v_add_co_u32_e32 v10, vcc, s47, v0
	s_mov_b32 s47, 0x108000
	s_nop 0
	v_addc_co_u32_e32 v11, vcc, 0, v1, vcc
	v_add_co_u32_e32 v12, vcc, s47, v0
	s_mov_b32 s47, 0x134000
	s_nop 0
	v_addc_co_u32_e32 v13, vcc, 0, v1, vcc
	v_add_co_u32_e32 v14, vcc, s47, v0
	s_mov_b32 s47, 0x160000
	s_nop 0
	v_addc_co_u32_e32 v15, vcc, 0, v1, vcc
	v_add_co_u32_e32 v26, vcc, s47, v0
	s_mov_b32 s47, 0x18c000
	s_nop 0
	v_addc_co_u32_e32 v27, vcc, 0, v1, vcc
	v_add_co_u32_e32 v28, vcc, s47, v0
	s_mov_b32 s47, 0x1b8000
	s_nop 0
	v_addc_co_u32_e32 v29, vcc, 0, v1, vcc
	v_add_co_u32_e32 v30, vcc, s47, v0
	s_mov_b32 s47, 0x1e4000
	s_nop 0
	v_addc_co_u32_e32 v31, vcc, 0, v1, vcc
	v_add_co_u32_e32 v32, vcc, s47, v0
	s_mov_b32 s47, 0x210000
	s_nop 0
	v_addc_co_u32_e32 v33, vcc, 0, v1, vcc
	v_add_co_u32_e32 v34, vcc, s47, v0
	s_nop 1
	v_addc_co_u32_e32 v35, vcc, 0, v1, vcc
	v_add_co_u32_e32 v36, vcc, 0x23c000, v0
	s_nop 1
	v_addc_co_u32_e32 v37, vcc, 0, v1, vcc
	v_add_co_u32_e32 v38, vcc, 0x268000, v0
	s_nop 1
	v_addc_co_u32_e32 v39, vcc, 0, v1, vcc
	v_add_co_u32_e32 v40, vcc, 0x294000, v0
	s_nop 1
	v_addc_co_u32_e32 v41, vcc, 0, v1, vcc
	global_load_dword v0, v[0:1], off nt
	s_nop 0
	global_load_dword v1, v[2:3], off nt
	s_nop 0
	global_load_dword v2, v[4:5], off nt
	global_load_dword v3, v[6:7], off nt
	s_nop 0
	global_load_dword v4, v[8:9], off nt
	global_load_dword v5, v[10:11], off nt
	global_load_dword v6, v[12:13], off nt
	global_load_dword v7, v[14:15], off nt
	s_nop 0
	global_load_dword v8, v[26:27], off nt
	global_load_dword v9, v[28:29], off nt
	global_load_dword v10, v[30:31], off nt
	global_load_dword v11, v[32:33], off nt
	global_load_dword v12, v[34:35], off nt
	global_load_dword v13, v[36:37], off nt
	global_load_dword v14, v[38:39], off nt
	global_load_dword v15, v[40:41], off nt
	s_branch .Ldu0_b115

.Ldw0_b118:
	s_waitcnt vmcnt(17)
	v_mov_b32_e32 v0, v208
	s_mov_b32 s24, s2
	s_barrier
	s_cmpk_gt_i32 s24, 0x57f
	s_cbranch_scc1 .Ldc_w0_done
	s_add_u32 s40, s58, 0
	s_mul_hi_i32 s26, s24, 0x2e8ba2e9
	s_addc_u32 s41, s59, 0
	s_lshr_b32 s27, s26, 31
	s_ashr_i32 s26, s26, 3
	s_add_i32 s26, s26, s27
	s_mul_i32 s27, s26, 44
	v_and_b32_e32 v20, 63, v0
	v_ashrrev_i32_e32 v23, 6, v0
	s_sub_i32 s27, s24, s27
	s_waitcnt vmcnt(15)
	v_lshl_or_b32 v2, s26, 6, v20
	s_waitcnt vmcnt(13)
	v_lshl_add_u32 v4, s27, 7, v23
	v_ashrrev_i32_e32 v3, 31, v2
	s_waitcnt vmcnt(12)
	v_ashrrev_i32_e32 v5, 31, v4
	v_lshl_add_u64 v[2:3], v[2:3], 2, s[40:41]
	v_lshlrev_b64 v[4:5], 13, v[4:5]
	v_lshl_add_u64 v[2:3], v[2:3], 0, v[4:5]
	v_add_co_u32_e32 v4, vcc, s67, v2
	s_mov_b32 s26, 0xb0000
	s_nop 0
	v_addc_co_u32_e32 v5, vcc, 0, v3, vcc
	s_waitcnt vmcnt(11)
	v_add_co_u32_e32 v6, vcc, s17, v2
	v_ashrrev_i32_e32 v21, 4, v0
	s_waitcnt vmcnt(10)
	v_addc_co_u32_e32 v7, vcc, 0, v3, vcc
	s_waitcnt vmcnt(9)
	v_add_co_u32_e32 v8, vcc, s74, v2
	s_mov_b32 s27, 0xf0000
	s_waitcnt vmcnt(8)
	v_addc_co_u32_e32 v9, vcc, 0, v3, vcc
	s_waitcnt vmcnt(7)
	v_add_co_u32_e32 v10, vcc, s20, v2
	v_lshlrev_b32_e32 v0, 3, v0
	s_waitcnt vmcnt(6)
	v_addc_co_u32_e32 v11, vcc, 0, v3, vcc
	s_waitcnt vmcnt(5)
	v_add_co_u32_e32 v12, vcc, s75, v2
	v_and_b32_e32 v22, 0x78, v0
	s_waitcnt vmcnt(4)
	v_addc_co_u32_e32 v13, vcc, 0, v3, vcc
	s_waitcnt vmcnt(3)
	v_add_co_u32_e32 v14, vcc, s21, v2
	v_lshlrev_b32_e32 v16, 1, v22
	s_waitcnt vmcnt(2)
	v_addc_co_u32_e32 v15, vcc, 0, v3, vcc
	v_add_co_u32_e32 v24, vcc, s30, v2
	v_lshl_add_u64 v[0:1], s[18:19], 0, v[16:17]
	s_nop 0
	v_addc_co_u32_e32 v25, vcc, 0, v3, vcc
	v_add_co_u32_e32 v26, vcc, s64, v2
	v_mul_u32_u24_e32 v22, 0x104, v22
	s_nop 0
	v_addc_co_u32_e32 v27, vcc, 0, v3, vcc
	v_add_co_u32_e32 v28, vcc, s31, v2
	s_mov_b64 s[42:43], 0
	s_nop 0
	v_addc_co_u32_e32 v29, vcc, 0, v3, vcc
	v_add_co_u32_e32 v30, vcc, s65, v2
	s_nop 1
	v_addc_co_u32_e32 v31, vcc, 0, v3, vcc
	v_add_co_u32_e32 v32, vcc, s26, v2
	s_mov_b32 s26, 0xd0000
	s_nop 0
	v_addc_co_u32_e32 v33, vcc, 0, v3, vcc
	v_add_co_u32_e32 v34, vcc, s66, v2
	s_nop 1
	v_addc_co_u32_e32 v35, vcc, 0, v3, vcc
	v_add_co_u32_e32 v36, vcc, s26, v2
	s_mov_b32 s26, 0xe0000
	s_nop 0
	v_addc_co_u32_e32 v37, vcc, 0, v3, vcc
	v_add_co_u32_e32 v38, vcc, s26, v2
	s_load_dword s28, s[62:63], 0x0
	s_load_dword s26, s[62:63], 0x10
	v_addc_co_u32_e32 v39, vcc, 0, v3, vcc
	v_add_co_u32_e32 v40, vcc, s27, v2
	s_waitcnt lgkmcnt(0)
	s_lshr_b32 s26, s26, 16
	s_cmp_lg_u32 s26, 0
	s_cselect_b64 s[26:27], -1, 0
	s_cmp_lg_u64 s[26:27], 0
	s_addc_u32 s26, s28, 0
	s_mov_b32 s26, s60
	s_mov_b64 s[28:29], 0x6f78000
	v_addc_co_u32_e32 v41, vcc, 0, v3, vcc
	v_lshl_add_u64 v[18:19], v[0:1], 0, s[28:29]
	global_load_dword v0, v[2:3], off nt
	global_load_dword v1, v[4:5], off nt
	s_nop 0
	global_load_dword v2, v[6:7], off nt
	global_load_dword v3, v[8:9], off nt
	global_load_dword v4, v[10:11], off nt
	global_load_dword v5, v[12:13], off nt
	s_nop 0
	global_load_dword v6, v[14:15], off nt
	global_load_dword v7, v[24:25], off nt
	global_load_dword v8, v[26:27], off nt
	global_load_dword v9, v[28:29], off nt
	global_load_dword v10, v[30:31], off nt
	global_load_dword v11, v[32:33], off nt
	global_load_dword v12, v[34:35], off nt
	global_load_dword v13, v[36:37], off nt
	global_load_dword v14, v[38:39], off nt
	global_load_dword v15, v[40:41], off nt
	s_movk_i32 s27, 0x104
	s_lshl_b32 s36, s26, 7
	v_mul_lo_u32 v16, v23, s27
	s_lshl_b32 s27, s24, 7
	v_add_u32_e32 v23, s36, v23
	s_branch .Ldw0_b121

.LBB0_1000:
	s_waitcnt vmcnt(0)
	s_barrier
	v_readlane_b32 s83, v255, 41
	s_cmp_lg_u32 s83, 0
	s_cbranch_scc1 .LBB0_1001
	s_cmp_gt_u32 s60, 64
	s_cselect_b32 s84, 64, 0
	s_cmp_lt_u32 s2, s84
	s_cbranch_scc1 .LBB0_1001
	s_sub_u32 s2, s2, s84
	s_sub_u32 s60, s60, s84
	v_writelane_b32 v255, s84, 47
	v_readlane_b32 s62, v255, 37
	v_readlane_b32 s63, v255, 38
	v_readlane_b32 s18, v255, 8
	v_readlane_b32 s19, v255, 9
	s_load_dwordx4 s[48:51], s[18:19], 0x48
	s_load_dwordx2 s[0:1], s[18:19], 0x68
	s_load_dwordx2 s[38:39], s[18:19], 0x88
	s_load_dwordx2 s[22:23], s[18:19], 0x98
	s_load_dwordx8 s[40:47], s[18:19], 0xb8
	s_load_dwordx4 s[56:59], s[18:19], 0xd8
	s_nop 0
	s_load_dwordx2 s[18:19], s[18:19], 0xf0
	v_mov_b32_e32 v0, v208
	s_mov_b32 s24, s2
	s_cmpk_gt_i32 s24, 0x3ff
	s_cbranch_scc1 .LBB0_96
	s_waitcnt lgkmcnt(0)
	s_add_u32 s48, s48, 0x2000000
	s_addc_u32 s49, s49, 0
	s_ashr_i32 s26, s24, 31
	s_lshr_b32 s26, s26, 28
	s_add_i32 s26, s24, s26
	s_lshl_b32 s27, s26, 2
	s_and_b32 s26, s26, 0x1fffff0
	v_ashrrev_i32_e32 v23, 6, v0
	s_sub_i32 s26, s24, s26
	v_mov_b32_e32 v1, s27
	s_movk_i32 s27, 0xffc0
	v_bfi_b32 v2, s27, v1, v0
	v_lshl_add_u32 v4, s26, 7, v23
	v_ashrrev_i32_e32 v3, 31, v2
	v_ashrrev_i32_e32 v5, 31, v4
	v_lshl_add_u64 v[2:3], v[2:3], 2, s[48:49]
	v_lshlrev_b64 v[4:5], 14, v[4:5]
	v_lshl_add_u64 v[2:3], v[2:3], 0, v[4:5]
	v_add_co_u32_e32 v4, vcc, s17, v2
	s_mov_b32 s26, 0xe0000
	s_nop 0
	v_addc_co_u32_e32 v5, vcc, 0, v3, vcc
	v_add_co_u32_e32 v6, vcc, s20, v2
	v_and_b32_e32 v20, 63, v0
	s_nop 0
	v_addc_co_u32_e32 v7, vcc, 0, v3, vcc
	v_add_co_u32_e32 v8, vcc, s21, v2
	v_ashrrev_i32_e32 v21, 4, v0
	s_nop 0
	v_addc_co_u32_e32 v9, vcc, 0, v3, vcc
	v_add_co_u32_e32 v10, vcc, s64, v2
	v_lshlrev_b32_e32 v0, 3, v0
	s_waitcnt vmcnt(6)
	v_addc_co_u32_e32 v11, vcc, 0, v3, vcc
	s_waitcnt vmcnt(5)
	v_add_co_u32_e32 v12, vcc, s65, v2
	v_and_b32_e32 v22, 0x78, v0
	s_waitcnt vmcnt(4)
	v_addc_co_u32_e32 v13, vcc, 0, v3, vcc
	v_add_co_u32_e32 v14, vcc, s66, v2
	s_waitcnt vmcnt(3)
	v_lshlrev_b32_e32 v16, 1, v22
	s_waitcnt vmcnt(2)
	v_addc_co_u32_e32 v15, vcc, 0, v3, vcc
	v_add_co_u32_e32 v24, vcc, s26, v2
	s_mov_b32 s26, 0x100000
	s_nop 0
	v_addc_co_u32_e32 v25, vcc, 0, v3, vcc
	v_add_co_u32_e32 v26, vcc, s26, v2
	s_mov_b32 s26, 0x120000
	s_nop 0
	v_addc_co_u32_e32 v27, vcc, 0, v3, vcc
	v_add_co_u32_e32 v28, vcc, s26, v2
	s_mov_b32 s26, 0x140000
	s_nop 0
	v_addc_co_u32_e32 v29, vcc, 0, v3, vcc
	v_add_co_u32_e32 v30, vcc, s26, v2
	s_mov_b32 s26, 0x160000
	s_nop 0
	v_addc_co_u32_e32 v31, vcc, 0, v3, vcc
	v_add_co_u32_e32 v32, vcc, s26, v2
	s_mov_b32 s26, 0x180000
	s_nop 0
	v_addc_co_u32_e32 v33, vcc, 0, v3, vcc
	v_add_co_u32_e32 v34, vcc, s26, v2
	s_mov_b32 s26, 0x1a0000
	s_nop 0
	v_addc_co_u32_e32 v35, vcc, 0, v3, vcc
	v_add_co_u32_e32 v36, vcc, s26, v2
	s_mov_b32 s26, 0x1c0000
	s_nop 0
	v_addc_co_u32_e32 v37, vcc, 0, v3, vcc
	v_add_co_u32_e32 v38, vcc, s26, v2
	s_mov_b32 s26, 0x1e0000
	s_nop 0
	v_addc_co_u32_e32 v39, vcc, 0, v3, vcc
	v_add_co_u32_e32 v40, vcc, s26, v2
	v_lshl_add_u64 v[0:1], s[18:19], 0, v[16:17]
	s_mov_b64 s[26:27], 0x378000
	v_addc_co_u32_e32 v41, vcc, 0, v3, vcc
	v_lshl_add_u64 v[18:19], v[0:1], 0, s[26:27]
	global_load_dword v0, v[2:3], off nt
	global_load_dword v1, v[4:5], off nt
	s_nop 0
	global_load_dword v2, v[6:7], off nt
	global_load_dword v3, v[8:9], off nt
	global_load_dword v4, v[10:11], off nt
	global_load_dword v5, v[12:13], off nt
	s_nop 0
	global_load_dword v6, v[14:15], off nt
	global_load_dword v7, v[24:25], off nt
	global_load_dword v8, v[26:27], off nt
	global_load_dword v9, v[28:29], off nt
	global_load_dword v10, v[30:31], off nt
	global_load_dword v11, v[32:33], off nt
	global_load_dword v12, v[34:35], off nt
	global_load_dword v13, v[36:37], off nt
	global_load_dword v14, v[38:39], off nt
	global_load_dword v15, v[40:41], off nt
	s_movk_i32 s26, 0x104
	s_lshl_b32 s27, s60, 7
	v_mul_lo_u32 v16, v23, s26
	v_mul_u32_u24_e32 v22, 0x104, v22
	s_lshl_b32 s26, s24, 7
	v_add_u32_e32 v23, s27, v23
	s_mov_b64 s[52:53], 0
	s_branch .LBB0_94

.LBB0_94:
	s_and_b64 s[28:29], s[52:53], exec
	s_cselect_b32 s28, 0x8200, 0
	s_add_i32 s37, s28, 0
	s_add_i32 s36, s24, s60
	s_cmpk_gt_i32 s36, 0x3ff
	v_lshlrev_b32_e32 v24, 2, v20
	s_cselect_b64 s[28:29], -1, 0
	v_add3_u32 v24, s37, v24, v16
	s_and_b64 vcc, exec, s[28:29]
	s_waitcnt vmcnt(15)
	ds_write_b32 v24, v0
	s_waitcnt vmcnt(14)
	ds_write_b32 v24, v1 offset:2080
	s_waitcnt vmcnt(13)
	ds_write_b32 v24, v2 offset:4160
	s_waitcnt vmcnt(12)
	ds_write_b32 v24, v3 offset:6240
	s_waitcnt vmcnt(11)
	ds_write_b32 v24, v4 offset:8320
	s_waitcnt vmcnt(10)
	ds_write_b32 v24, v5 offset:10400
	s_waitcnt vmcnt(9)
	ds_write_b32 v24, v6 offset:12480
	s_waitcnt vmcnt(8)
	ds_write_b32 v24, v7 offset:14560
	s_waitcnt vmcnt(7)
	ds_write_b32 v24, v8 offset:16640
	s_waitcnt vmcnt(6)
	ds_write_b32 v24, v9 offset:18720
	s_waitcnt vmcnt(5)
	ds_write_b32 v24, v10 offset:20800
	s_waitcnt vmcnt(4)
	ds_write_b32 v24, v11 offset:22880
	s_waitcnt vmcnt(3)
	ds_write_b32 v24, v12 offset:24960
	s_waitcnt vmcnt(2)
	ds_write_b32 v24, v13 offset:27040
	s_waitcnt vmcnt(1)
	ds_write_b32 v24, v14 offset:29120
	s_waitcnt vmcnt(0)
	ds_write_b32 v24, v15 offset:31200
	s_cbranch_vccnz .LBB0_93
	s_ashr_i32 s83, s36, 31
	s_lshr_b32 s83, s83, 28
	s_add_i32 s83, s36, s83
	s_ashr_i32 s83, s83, 4
	v_lshl_or_b32 v0, s83, 6, v20
	v_add_u32_e32 v2, s26, v23
	s_lshl_b32 s83, s83, 11
	v_subrev_u32_e32 v2, s83, v2
	v_ashrrev_i32_e32 v1, 31, v0
	v_ashrrev_i32_e32 v3, 31, v2
	v_lshl_add_u64 v[0:1], v[0:1], 2, s[48:49]
	v_lshlrev_b64 v[2:3], 14, v[2:3]
	v_lshl_add_u64 v[0:1], v[0:1], 0, v[2:3]
	v_add_co_u32_e32 v2, vcc, s17, v0
	s_mov_b32 s83, 0xe0000
	s_nop 0
	v_addc_co_u32_e32 v3, vcc, 0, v1, vcc
	v_add_co_u32_e32 v4, vcc, s20, v0
	s_nop 1
	v_addc_co_u32_e32 v5, vcc, 0, v1, vcc
	v_add_co_u32_e32 v6, vcc, s21, v0
	s_nop 1
	v_addc_co_u32_e32 v7, vcc, 0, v1, vcc
	v_add_co_u32_e32 v8, vcc, s64, v0
	s_nop 1
	v_addc_co_u32_e32 v9, vcc, 0, v1, vcc
	v_add_co_u32_e32 v10, vcc, s65, v0
	s_nop 1
	v_addc_co_u32_e32 v11, vcc, 0, v1, vcc
	v_add_co_u32_e32 v12, vcc, s66, v0
	s_nop 1
	v_addc_co_u32_e32 v13, vcc, 0, v1, vcc
	v_add_co_u32_e32 v14, vcc, s83, v0
	s_mov_b32 s83, 0x100000
	s_nop 0
	v_addc_co_u32_e32 v15, vcc, 0, v1, vcc
	v_add_co_u32_e32 v24, vcc, s83, v0
	s_mov_b32 s83, 0x120000
	s_nop 0
	v_addc_co_u32_e32 v25, vcc, 0, v1, vcc
	v_add_co_u32_e32 v26, vcc, s83, v0
	s_mov_b32 s83, 0x140000
	s_nop 0
	v_addc_co_u32_e32 v27, vcc, 0, v1, vcc
	v_add_co_u32_e32 v28, vcc, s83, v0
	s_mov_b32 s83, 0x160000
	s_nop 0
	v_addc_co_u32_e32 v29, vcc, 0, v1, vcc
	v_add_co_u32_e32 v30, vcc, s83, v0
	s_mov_b32 s83, 0x180000
	s_nop 0
	v_addc_co_u32_e32 v31, vcc, 0, v1, vcc
	v_add_co_u32_e32 v32, vcc, s83, v0
	s_nop 1
	v_addc_co_u32_e32 v33, vcc, 0, v1, vcc
	v_add_co_u32_e32 v34, vcc, 0x1a0000, v0
	s_nop 1
	v_addc_co_u32_e32 v35, vcc, 0, v1, vcc
	v_add_co_u32_e32 v36, vcc, 0x1c0000, v0
	s_nop 1
	v_addc_co_u32_e32 v37, vcc, 0, v1, vcc
	v_add_co_u32_e32 v38, vcc, 0x1e0000, v0
	s_nop 1
	v_addc_co_u32_e32 v39, vcc, 0, v1, vcc
	global_load_dword v0, v[0:1], off nt
	s_nop 0
	global_load_dword v1, v[2:3], off nt
	s_nop 0
	global_load_dword v2, v[4:5], off nt
	global_load_dword v3, v[6:7], off nt
	s_nop 0
	global_load_dword v4, v[8:9], off nt
	global_load_dword v5, v[10:11], off nt
	global_load_dword v6, v[12:13], off nt
	global_load_dword v7, v[14:15], off nt
	s_nop 0
	global_load_dword v8, v[24:25], off nt
	global_load_dword v9, v[26:27], off nt
	global_load_dword v10, v[28:29], off nt
	global_load_dword v11, v[30:31], off nt
	global_load_dword v12, v[32:33], off nt
	global_load_dword v13, v[34:35], off nt
	global_load_dword v14, v[36:37], off nt
	global_load_dword v15, v[38:39], off nt
	s_branch .LBB0_93
.LBB0_96:
	s_waitcnt vmcnt(17)
	v_mov_b32_e32 v0, v208
	s_mov_b32 s24, s2
	s_waitcnt lgkmcnt(0)
	s_barrier
	s_cmpk_gt_i32 s24, 0x7ff
	s_cbranch_scc1 .LBB0_101
	s_add_u32 s42, s42, 0x4000000
	s_addc_u32 s43, s43, 0
	s_ashr_i32 s26, s24, 31
	s_lshr_b32 s26, s26, 28
	s_add_i32 s26, s24, s26
	s_ashr_i32 s27, s26, 4
	v_and_b32_e32 v20, 63, v0
	s_lshl_b32 s28, s27, 6
	s_waitcnt vmcnt(16)
	v_or_b32_e32 v1, s28, v20
	v_bfe_u32 v23, v0, 4, 1
	v_ashrrev_i32_e32 v26, 6, v0
	v_and_b32_e32 v21, 15, v0
	v_ashrrev_i32_e32 v22, 4, v0
	s_waitcnt vmcnt(15)
	v_and_or_b32 v2, s27, 2, v23
	s_ashr_i32 s27, s28, 2
	v_lshrrev_b32_e32 v0, 1, v1
	s_andn2_b32 s27, s27, 63
	v_and_b32_e32 v0, 48, v0
	s_and_b32 s26, s26, 0x1fffff0
	v_or3_b32 v0, s27, v0, v21
	s_waitcnt vmcnt(3)
	v_lshlrev_b32_e32 v16, 13, v2
	s_sub_i32 s26, s24, s26
	v_lshl_add_u64 v[2:3], s[42:43], 0, v[16:17]
	v_ashrrev_i32_e32 v1, 31, v0
	v_lshl_add_u64 v[0:1], v[0:1], 2, v[2:3]
	v_lshl_add_u32 v2, s26, 7, v26
	v_ashrrev_i32_e32 v3, 31, v2
	v_lshlrev_b64 v[2:3], 15, v[2:3]
	v_lshl_add_u64 v[0:1], v[0:1], 0, v[2:3]
	v_add_co_u32_e32 v2, vcc, s20, v0
	s_mov_b32 s26, 0x100000
	s_nop 0
	v_addc_co_u32_e32 v3, vcc, 0, v1, vcc
	v_add_co_u32_e32 v4, vcc, s64, v0
	v_lshlrev_b32_e32 v16, 4, v21
	s_nop 0
	v_addc_co_u32_e32 v5, vcc, 0, v1, vcc
	v_add_co_u32_e32 v6, vcc, s66, v0
	v_lshl_add_u64 v[18:19], s[18:19], 0, v[16:17]
	s_nop 0
	v_addc_co_u32_e32 v7, vcc, 0, v1, vcc
	v_add_co_u32_e32 v8, vcc, s26, v0
	s_mov_b32 s26, 0x140000
	s_nop 0
	v_addc_co_u32_e32 v9, vcc, 0, v1, vcc
	v_add_co_u32_e32 v10, vcc, s26, v0
	s_mov_b32 s26, 0x180000
	s_nop 0
	v_addc_co_u32_e32 v11, vcc, 0, v1, vcc
	v_add_co_u32_e32 v12, vcc, s26, v0
	s_mov_b32 s26, 0x1c0000
	s_nop 0
	v_addc_co_u32_e32 v13, vcc, 0, v1, vcc
	v_add_co_u32_e32 v14, vcc, s26, v0
	s_mov_b32 s26, 0x200000
	s_waitcnt vmcnt(2)
	v_addc_co_u32_e32 v15, vcc, 0, v1, vcc
	v_add_co_u32_e32 v28, vcc, s26, v0
	s_mov_b32 s26, 0x240000
	s_nop 0
	v_addc_co_u32_e32 v29, vcc, 0, v1, vcc
	v_add_co_u32_e32 v30, vcc, s26, v0
	s_mov_b32 s26, 0x280000
	s_nop 0
	v_addc_co_u32_e32 v31, vcc, 0, v1, vcc
	v_add_co_u32_e32 v32, vcc, s26, v0
	s_mov_b32 s26, 0x2c0000
	s_nop 0
	v_addc_co_u32_e32 v33, vcc, 0, v1, vcc
	v_add_co_u32_e32 v34, vcc, s26, v0
	s_mov_b32 s26, 0x300000
	s_nop 0
	v_addc_co_u32_e32 v35, vcc, 0, v1, vcc
	v_add_co_u32_e32 v36, vcc, s26, v0
	s_mov_b32 s26, 0x340000
	s_nop 0
	v_addc_co_u32_e32 v37, vcc, 0, v1, vcc
	v_add_co_u32_e32 v38, vcc, s26, v0
	s_mov_b32 s26, 0x380000
	s_nop 0
	v_addc_co_u32_e32 v39, vcc, 0, v1, vcc
	v_add_co_u32_e32 v40, vcc, s26, v0
	s_mov_b32 s26, 0x3c0000
	s_nop 0
	v_addc_co_u32_e32 v41, vcc, 0, v1, vcc
	v_add_co_u32_e32 v42, vcc, s26, v0
	s_mov_b64 s[26:27], 0x1378000
	s_nop 0
	v_addc_co_u32_e32 v43, vcc, 0, v1, vcc
	global_load_dword v0, v[0:1], off nt
	s_nop 0
	global_load_dword v1, v[2:3], off nt
	s_nop 0
	global_load_dword v2, v[4:5], off nt
	global_load_dword v3, v[6:7], off nt
	s_nop 0
	global_load_dword v4, v[8:9], off nt
	global_load_dword v5, v[10:11], off nt
	global_load_dword v6, v[12:13], off nt
	global_load_dword v7, v[14:15], off nt
	s_nop 0
	global_load_dword v8, v[28:29], off nt
	global_load_dword v9, v[30:31], off nt
	global_load_dword v10, v[32:33], off nt
	global_load_dword v11, v[34:35], off nt
	global_load_dword v12, v[36:37], off nt
	global_load_dword v13, v[38:39], off nt
	global_load_dword v14, v[40:41], off nt
	global_load_dword v15, v[42:43], off nt
	v_lshl_add_u64 v[18:19], v[18:19], 0, s[26:27]
	s_movk_i32 s26, 0x104
	s_lshl_b32 s27, s60, 7
	v_mul_lo_u32 v24, v26, s26
	v_mul_u32_u24_e32 v25, 0x820, v21
	s_lshl_b32 s26, s24, 7
	v_add_u32_e32 v26, s27, v26
	s_mov_b64 s[48:49], 0
	s_branch .LBB0_99

.LBB0_103:
	s_waitcnt vmcnt(17)
	v_mov_b32_e32 v0, v208
	s_mov_b32 s48, s2
	s_cmpk_gt_i32 s48, 0x7f
	s_cbranch_scc1 .LBB0_102
	s_lshl_b64 s[28:29], s[24:25], 22
	s_add_u32 s40, s36, s28
	s_addc_u32 s41, s37, s29
	s_lshl_b64 s[28:29], s[24:25], 21
	s_add_u32 s28, s26, s28
	s_addc_u32 s29, s27, s29
	s_ashr_i32 s42, s48, 31
	s_lshr_b32 s42, s42, 30
	s_add_i32 s42, s48, s42
	s_lshl_b32 s43, s42, 4
	s_and_b32 s42, s42, 0x1fffffc
	s_waitcnt vmcnt(16)
	v_ashrrev_i32_e32 v1, 6, v0
	s_sub_i32 s42, s48, s42
	s_waitcnt vmcnt(15)
	v_mov_b32_e32 v2, s43
	s_movk_i32 s43, 0xffc0
	v_bfi_b32 v2, s43, v2, v0
	s_waitcnt vmcnt(13)
	v_lshl_add_u32 v4, s42, 7, v1
	v_ashrrev_i32_e32 v3, 31, v2
	s_waitcnt vmcnt(12)
	v_ashrrev_i32_e32 v5, 31, v4
	v_lshl_add_u64 v[2:3], v[2:3], 2, s[40:41]
	v_lshlrev_b64 v[4:5], 13, v[4:5]
	v_lshl_add_u64 v[2:3], v[2:3], 0, v[4:5]
	v_add_co_u32_e32 v4, vcc, s67, v2
	s_mov_b32 s42, 0xb0000
	s_nop 0
	v_addc_co_u32_e32 v5, vcc, 0, v3, vcc
	s_waitcnt vmcnt(11)
	v_add_co_u32_e32 v6, vcc, s17, v2
	s_mov_b32 s43, 0xf0000
	s_waitcnt vmcnt(10)
	v_addc_co_u32_e32 v7, vcc, 0, v3, vcc
	s_waitcnt vmcnt(9)
	v_add_co_u32_e32 v8, vcc, s74, v2
	v_and_b32_e32 v20, 63, v0
	s_waitcnt vmcnt(8)
	v_addc_co_u32_e32 v9, vcc, 0, v3, vcc
	s_waitcnt vmcnt(7)
	v_add_co_u32_e32 v10, vcc, s20, v2
	v_ashrrev_i32_e32 v21, 4, v0
	s_waitcnt vmcnt(6)
	v_addc_co_u32_e32 v11, vcc, 0, v3, vcc
	s_waitcnt vmcnt(5)
	v_add_co_u32_e32 v12, vcc, s75, v2
	v_lshlrev_b32_e32 v0, 3, v0
	s_waitcnt vmcnt(4)
	v_addc_co_u32_e32 v13, vcc, 0, v3, vcc
	s_waitcnt vmcnt(3)
	v_add_co_u32_e32 v14, vcc, s21, v2
	v_and_b32_e32 v0, 0x78, v0
	s_waitcnt vmcnt(2)
	v_addc_co_u32_e32 v15, vcc, 0, v3, vcc
	v_add_co_u32_e32 v24, vcc, s30, v2
	v_lshlrev_b32_e32 v16, 1, v0
	s_nop 0
	v_addc_co_u32_e32 v25, vcc, 0, v3, vcc
	v_add_co_u32_e32 v26, vcc, s64, v2
	v_lshl_add_u64 v[18:19], s[28:29], 0, v[16:17]
	s_nop 0
	v_addc_co_u32_e32 v27, vcc, 0, v3, vcc
	v_add_co_u32_e32 v28, vcc, s31, v2
	s_movk_i32 s28, 0x104
	s_nop 0
	v_addc_co_u32_e32 v29, vcc, 0, v3, vcc
	v_add_co_u32_e32 v30, vcc, s65, v2
	v_mul_lo_u32 v16, v1, s28
	s_nop 0
	v_addc_co_u32_e32 v31, vcc, 0, v3, vcc
	v_add_co_u32_e32 v32, vcc, s42, v2
	s_mov_b32 s42, 0xd0000
	s_nop 0
	v_addc_co_u32_e32 v33, vcc, 0, v3, vcc
	v_add_co_u32_e32 v34, vcc, s66, v2
	v_mul_u32_u24_e32 v22, 0x104, v0
	s_nop 0
	v_addc_co_u32_e32 v35, vcc, 0, v3, vcc
	v_add_co_u32_e32 v36, vcc, s42, v2
	s_mov_b32 s42, 0xe0000
	s_nop 0
	v_addc_co_u32_e32 v37, vcc, 0, v3, vcc
	v_add_co_u32_e32 v38, vcc, s42, v2
	s_load_dword s49, s[62:63], 0x0
	s_load_dword s42, s[62:63], 0x10
	v_addc_co_u32_e32 v39, vcc, 0, v3, vcc
	v_add_co_u32_e32 v40, vcc, s43, v2
	s_waitcnt lgkmcnt(0)
	s_lshr_b32 s42, s42, 16
	s_cmp_lg_u32 s42, 0
	s_cselect_b64 s[42:43], -1, 0
	s_cmp_lg_u64 s[42:43], 0
	s_addc_u32 s49, s49, 0
	s_lshl_b32 s53, s49, 7
	v_addc_co_u32_e32 v41, vcc, 0, v3, vcc
	v_add_u32_e32 v23, s53, v1
	global_load_dword v0, v[2:3], off nt
	global_load_dword v1, v[4:5], off nt
	s_nop 0
	global_load_dword v2, v[6:7], off nt
	global_load_dword v3, v[8:9], off nt
	global_load_dword v4, v[10:11], off nt
	global_load_dword v5, v[12:13], off nt
	s_nop 0
	global_load_dword v6, v[14:15], off nt
	global_load_dword v7, v[24:25], off nt
	global_load_dword v8, v[26:27], off nt
	global_load_dword v9, v[28:29], off nt
	global_load_dword v10, v[30:31], off nt
	global_load_dword v11, v[32:33], off nt
	global_load_dword v12, v[34:35], off nt
	global_load_dword v13, v[36:37], off nt
	global_load_dword v14, v[38:39], off nt
	global_load_dword v15, v[40:41], off nt
	s_lshl_b32 s52, s48, 7
	s_mov_b64 s[42:43], 0
	s_branch .LBB0_106

.LBB0_106:
	s_and_b64 s[28:29], s[42:43], exec
	s_cselect_b32 s28, 0x8200, 0
	s_add_i32 s84, s28, 0
	s_add_i32 s83, s49, s48
	s_cmpk_gt_i32 s83, 0x7f
	v_lshlrev_b32_e32 v24, 2, v20
	s_cselect_b64 s[28:29], -1, 0
	v_add3_u32 v24, s84, v24, v16
	s_and_b64 vcc, exec, s[28:29]
	s_waitcnt vmcnt(15)
	ds_write_b32 v24, v0
	s_waitcnt vmcnt(14)
	ds_write_b32 v24, v1 offset:2080
	s_waitcnt vmcnt(13)
	ds_write_b32 v24, v2 offset:4160
	s_waitcnt vmcnt(12)
	ds_write_b32 v24, v3 offset:6240
	s_waitcnt vmcnt(11)
	ds_write_b32 v24, v4 offset:8320
	s_waitcnt vmcnt(10)
	ds_write_b32 v24, v5 offset:10400
	s_waitcnt vmcnt(9)
	ds_write_b32 v24, v6 offset:12480
	s_waitcnt vmcnt(8)
	ds_write_b32 v24, v7 offset:14560
	s_waitcnt vmcnt(7)
	ds_write_b32 v24, v8 offset:16640
	s_waitcnt vmcnt(6)
	ds_write_b32 v24, v9 offset:18720
	s_waitcnt vmcnt(5)
	ds_write_b32 v24, v10 offset:20800
	s_waitcnt vmcnt(4)
	ds_write_b32 v24, v11 offset:22880
	s_waitcnt vmcnt(3)
	ds_write_b32 v24, v12 offset:24960
	s_waitcnt vmcnt(2)
	ds_write_b32 v24, v13 offset:27040
	s_waitcnt vmcnt(1)
	ds_write_b32 v24, v14 offset:29120
	s_waitcnt vmcnt(0)
	ds_write_b32 v24, v15 offset:31200
	s_cbranch_vccnz .LBB0_105
	s_ashr_i32 s85, s83, 31
	s_lshr_b32 s85, s85, 30
	s_add_i32 s85, s83, s85
	s_ashr_i32 s85, s85, 2
	v_lshl_or_b32 v0, s85, 6, v20
	v_add_u32_e32 v2, s52, v23
	s_lshl_b32 s85, s85, 9
	v_subrev_u32_e32 v2, s85, v2
	v_ashrrev_i32_e32 v1, 31, v0
	v_ashrrev_i32_e32 v3, 31, v2
	v_lshl_add_u64 v[0:1], v[0:1], 2, s[40:41]
	v_lshlrev_b64 v[2:3], 13, v[2:3]
	v_lshl_add_u64 v[0:1], v[0:1], 0, v[2:3]
	v_add_co_u32_e32 v2, vcc, s67, v0
	s_nop 1
	v_addc_co_u32_e32 v3, vcc, 0, v1, vcc
	v_add_co_u32_e32 v4, vcc, s17, v0
	s_nop 1
	v_addc_co_u32_e32 v5, vcc, 0, v1, vcc
	v_add_co_u32_e32 v6, vcc, s74, v0
	s_nop 1
	v_addc_co_u32_e32 v7, vcc, 0, v1, vcc
	v_add_co_u32_e32 v8, vcc, s20, v0
	s_nop 1
	v_addc_co_u32_e32 v9, vcc, 0, v1, vcc
	v_add_co_u32_e32 v10, vcc, s75, v0
	s_nop 1
	v_addc_co_u32_e32 v11, vcc, 0, v1, vcc
	v_add_co_u32_e32 v12, vcc, s21, v0
	s_nop 1
	v_addc_co_u32_e32 v13, vcc, 0, v1, vcc
	v_add_co_u32_e32 v14, vcc, s30, v0
	s_nop 1
	v_addc_co_u32_e32 v15, vcc, 0, v1, vcc
	v_add_co_u32_e32 v24, vcc, s64, v0
	s_nop 1
	v_addc_co_u32_e32 v25, vcc, 0, v1, vcc
	v_add_co_u32_e32 v26, vcc, s31, v0
	s_nop 1
	v_addc_co_u32_e32 v27, vcc, 0, v1, vcc
	v_add_co_u32_e32 v28, vcc, s65, v0
	s_nop 1
	v_addc_co_u32_e32 v29, vcc, 0, v1, vcc
	v_add_co_u32_e32 v30, vcc, 0xb0000, v0
	s_nop 1
	v_addc_co_u32_e32 v31, vcc, 0, v1, vcc
	v_add_co_u32_e32 v32, vcc, s66, v0
	s_nop 1
	v_addc_co_u32_e32 v33, vcc, 0, v1, vcc
	v_add_co_u32_e32 v34, vcc, 0xd0000, v0
	s_nop 1
	v_addc_co_u32_e32 v35, vcc, 0, v1, vcc
	v_add_co_u32_e32 v36, vcc, 0xe0000, v0
	s_nop 1
	v_addc_co_u32_e32 v37, vcc, 0, v1, vcc
	v_add_co_u32_e32 v38, vcc, 0xf0000, v0
	s_nop 1
	v_addc_co_u32_e32 v39, vcc, 0, v1, vcc
	global_load_dword v0, v[0:1], off nt
	s_nop 0
	global_load_dword v1, v[2:3], off nt
	s_nop 0
	global_load_dword v2, v[4:5], off nt
	global_load_dword v3, v[6:7], off nt
	s_nop 0
	global_load_dword v4, v[8:9], off nt
	global_load_dword v5, v[10:11], off nt
	global_load_dword v6, v[12:13], off nt
	global_load_dword v7, v[14:15], off nt
	s_nop 0
	global_load_dword v8, v[24:25], off nt
	global_load_dword v9, v[26:27], off nt
	global_load_dword v10, v[28:29], off nt
	global_load_dword v11, v[30:31], off nt
	global_load_dword v12, v[32:33], off nt
	global_load_dword v13, v[34:35], off nt
	global_load_dword v14, v[36:37], off nt
	global_load_dword v15, v[38:39], off nt
	s_branch .LBB0_105
.LBB0_108:
	s_waitcnt vmcnt(17)
	v_mov_b32_e32 v0, v208
	s_mov_b32 s24, s2
	s_cmpk_gt_i32 s24, 0x1ff
	s_cbranch_scc1 .LBB0_113
	s_add_u32 s40, s44, 0x1000000
	s_addc_u32 s41, s45, 0
	s_ashr_i32 s26, s24, 31
	s_lshr_b32 s26, s26, 28
	s_add_i32 s26, s24, s26
	s_lshl_b32 s27, s26, 2
	s_and_b32 s26, s26, 0x1fffff0
	v_ashrrev_i32_e32 v23, 6, v0
	s_sub_i32 s26, s24, s26
	s_waitcnt vmcnt(16)
	v_mov_b32_e32 v1, s27
	s_movk_i32 s27, 0xffc0
	s_waitcnt vmcnt(15)
	v_bfi_b32 v2, s27, v1, v0
	s_waitcnt vmcnt(13)
	v_lshl_add_u32 v4, s26, 7, v23
	v_ashrrev_i32_e32 v3, 31, v2
	s_waitcnt vmcnt(12)
	v_ashrrev_i32_e32 v5, 31, v4
	v_lshl_add_u64 v[2:3], v[2:3], 2, s[40:41]
	v_lshlrev_b64 v[4:5], 13, v[4:5]
	v_lshl_add_u64 v[2:3], v[2:3], 0, v[4:5]
	v_add_co_u32_e32 v4, vcc, s67, v2
	s_mov_b32 s26, 0xb0000
	s_nop 0
	v_addc_co_u32_e32 v5, vcc, 0, v3, vcc
	s_waitcnt vmcnt(11)
	v_add_co_u32_e32 v6, vcc, s17, v2
	v_and_b32_e32 v20, 63, v0
	s_waitcnt vmcnt(10)
	v_addc_co_u32_e32 v7, vcc, 0, v3, vcc
	s_waitcnt vmcnt(9)
	v_add_co_u32_e32 v8, vcc, s74, v2
	v_ashrrev_i32_e32 v21, 4, v0
	s_waitcnt vmcnt(8)
	v_addc_co_u32_e32 v9, vcc, 0, v3, vcc
	s_waitcnt vmcnt(7)
	v_add_co_u32_e32 v10, vcc, s20, v2
	s_mov_b32 s27, 0xf0000
	s_waitcnt vmcnt(6)
	v_addc_co_u32_e32 v11, vcc, 0, v3, vcc
	s_waitcnt vmcnt(5)
	v_add_co_u32_e32 v12, vcc, s75, v2
	v_lshlrev_b32_e32 v0, 3, v0
	s_waitcnt vmcnt(4)
	v_addc_co_u32_e32 v13, vcc, 0, v3, vcc
	s_waitcnt vmcnt(3)
	v_add_co_u32_e32 v14, vcc, s21, v2
	v_and_b32_e32 v22, 0x78, v0
	s_waitcnt vmcnt(2)
	v_addc_co_u32_e32 v15, vcc, 0, v3, vcc
	v_add_co_u32_e32 v24, vcc, s30, v2
	v_lshlrev_b32_e32 v16, 1, v22
	s_nop 0
	v_addc_co_u32_e32 v25, vcc, 0, v3, vcc
	v_add_co_u32_e32 v26, vcc, s64, v2
	v_lshl_add_u64 v[0:1], s[18:19], 0, v[16:17]
	s_nop 0
	v_addc_co_u32_e32 v27, vcc, 0, v3, vcc
	v_add_co_u32_e32 v28, vcc, s31, v2
	v_mul_u32_u24_e32 v22, 0x104, v22
	s_nop 0
	v_addc_co_u32_e32 v29, vcc, 0, v3, vcc
	v_add_co_u32_e32 v30, vcc, s65, v2
	s_mov_b64 s[42:43], 0
	s_nop 0
	v_addc_co_u32_e32 v31, vcc, 0, v3, vcc
	v_add_co_u32_e32 v32, vcc, s26, v2
	s_mov_b32 s26, 0xd0000
	s_nop 0
	v_addc_co_u32_e32 v33, vcc, 0, v3, vcc
	v_add_co_u32_e32 v34, vcc, s66, v2
	s_nop 1
	v_addc_co_u32_e32 v35, vcc, 0, v3, vcc
	v_add_co_u32_e32 v36, vcc, s26, v2
	s_mov_b32 s26, 0xe0000
	s_nop 0
	v_addc_co_u32_e32 v37, vcc, 0, v3, vcc
	v_add_co_u32_e32 v38, vcc, s26, v2
	s_load_dword s28, s[62:63], 0x0
	s_load_dword s26, s[62:63], 0x10
	v_addc_co_u32_e32 v39, vcc, 0, v3, vcc
	v_add_co_u32_e32 v40, vcc, s27, v2
	s_waitcnt lgkmcnt(0)
	s_lshr_b32 s26, s26, 16
	s_cmp_lg_u32 s26, 0
	s_cselect_b64 s[26:27], -1, 0
	s_cmp_lg_u64 s[26:27], 0
	s_addc_u32 s26, s28, 0
	s_mov_b32 s26, s60
	s_mov_b64 s[28:29], 0x3b78000
	v_addc_co_u32_e32 v41, vcc, 0, v3, vcc
	v_lshl_add_u64 v[18:19], v[0:1], 0, s[28:29]
	global_load_dword v0, v[2:3], off nt
	global_load_dword v1, v[4:5], off nt
	s_nop 0
	global_load_dword v2, v[6:7], off nt
	global_load_dword v3, v[8:9], off nt
	global_load_dword v4, v[10:11], off nt
	global_load_dword v5, v[12:13], off nt
	s_nop 0
	global_load_dword v6, v[14:15], off nt
	global_load_dword v7, v[24:25], off nt
	global_load_dword v8, v[26:27], off nt
	global_load_dword v9, v[28:29], off nt
	global_load_dword v10, v[30:31], off nt
	global_load_dword v11, v[32:33], off nt
	global_load_dword v12, v[34:35], off nt
	global_load_dword v13, v[36:37], off nt
	global_load_dword v14, v[38:39], off nt
	global_load_dword v15, v[40:41], off nt
	s_movk_i32 s27, 0x104
	s_lshl_b32 s36, s26, 7
	v_mul_lo_u32 v16, v23, s27
	s_lshl_b32 s27, s24, 7
	v_add_u32_e32 v23, s36, v23
	s_branch .LBB0_111

.LBB0_111:
	s_and_b64 s[28:29], s[42:43], exec
	s_cselect_b32 s28, 0x8200, 0
	s_add_i32 s44, s28, 0
	s_add_i32 s37, s26, s24
	s_cmpk_gt_i32 s37, 0x1ff
	v_lshlrev_b32_e32 v24, 2, v20
	s_cselect_b64 s[28:29], -1, 0
	v_add3_u32 v24, s44, v24, v16
	s_and_b64 vcc, exec, s[28:29]
	s_waitcnt vmcnt(15)
	ds_write_b32 v24, v0
	s_waitcnt vmcnt(14)
	ds_write_b32 v24, v1 offset:2080
	s_waitcnt vmcnt(13)
	ds_write_b32 v24, v2 offset:4160
	s_waitcnt vmcnt(12)
	ds_write_b32 v24, v3 offset:6240
	s_waitcnt vmcnt(11)
	ds_write_b32 v24, v4 offset:8320
	s_waitcnt vmcnt(10)
	ds_write_b32 v24, v5 offset:10400
	s_waitcnt vmcnt(9)
	ds_write_b32 v24, v6 offset:12480
	s_waitcnt vmcnt(8)
	ds_write_b32 v24, v7 offset:14560
	s_waitcnt vmcnt(7)
	ds_write_b32 v24, v8 offset:16640
	s_waitcnt vmcnt(6)
	ds_write_b32 v24, v9 offset:18720
	s_waitcnt vmcnt(5)
	ds_write_b32 v24, v10 offset:20800
	s_waitcnt vmcnt(4)
	ds_write_b32 v24, v11 offset:22880
	s_waitcnt vmcnt(3)
	ds_write_b32 v24, v12 offset:24960
	s_waitcnt vmcnt(2)
	ds_write_b32 v24, v13 offset:27040
	s_waitcnt vmcnt(1)
	ds_write_b32 v24, v14 offset:29120
	s_waitcnt vmcnt(0)
	ds_write_b32 v24, v15 offset:31200
	s_cbranch_vccnz .LBB0_110
	s_ashr_i32 s45, s37, 31
	s_lshr_b32 s45, s45, 28
	s_add_i32 s45, s37, s45
	s_ashr_i32 s45, s45, 4
	v_lshl_or_b32 v0, s45, 6, v20
	v_add_u32_e32 v2, s27, v23
	s_lshl_b32 s45, s45, 11
	v_subrev_u32_e32 v2, s45, v2
	v_ashrrev_i32_e32 v1, 31, v0
	v_ashrrev_i32_e32 v3, 31, v2
	v_lshl_add_u64 v[0:1], v[0:1], 2, s[40:41]
	v_lshlrev_b64 v[2:3], 13, v[2:3]
	v_lshl_add_u64 v[0:1], v[0:1], 0, v[2:3]
	v_add_co_u32_e32 v2, vcc, s67, v0
	s_nop 1
	v_addc_co_u32_e32 v3, vcc, 0, v1, vcc
	v_add_co_u32_e32 v4, vcc, s17, v0
	s_nop 1
	v_addc_co_u32_e32 v5, vcc, 0, v1, vcc
	v_add_co_u32_e32 v6, vcc, s74, v0
	s_nop 1
	v_addc_co_u32_e32 v7, vcc, 0, v1, vcc
	v_add_co_u32_e32 v8, vcc, s20, v0
	s_nop 1
	v_addc_co_u32_e32 v9, vcc, 0, v1, vcc
	v_add_co_u32_e32 v10, vcc, s75, v0
	s_nop 1
	v_addc_co_u32_e32 v11, vcc, 0, v1, vcc
	v_add_co_u32_e32 v12, vcc, s21, v0
	s_nop 1
	v_addc_co_u32_e32 v13, vcc, 0, v1, vcc
	v_add_co_u32_e32 v14, vcc, s30, v0
	s_nop 1
	v_addc_co_u32_e32 v15, vcc, 0, v1, vcc
	v_add_co_u32_e32 v24, vcc, s64, v0
	s_nop 1
	v_addc_co_u32_e32 v25, vcc, 0, v1, vcc
	v_add_co_u32_e32 v26, vcc, s31, v0
	s_nop 1
	v_addc_co_u32_e32 v27, vcc, 0, v1, vcc
	v_add_co_u32_e32 v28, vcc, s65, v0
	s_nop 1
	v_addc_co_u32_e32 v29, vcc, 0, v1, vcc
	v_add_co_u32_e32 v30, vcc, 0xb0000, v0
	s_nop 1
	v_addc_co_u32_e32 v31, vcc, 0, v1, vcc
	v_add_co_u32_e32 v32, vcc, s66, v0
	s_nop 1
	v_addc_co_u32_e32 v33, vcc, 0, v1, vcc
	v_add_co_u32_e32 v34, vcc, 0xd0000, v0
	s_nop 1
	v_addc_co_u32_e32 v35, vcc, 0, v1, vcc
	v_add_co_u32_e32 v36, vcc, 0xe0000, v0
	s_nop 1
	v_addc_co_u32_e32 v37, vcc, 0, v1, vcc
	v_add_co_u32_e32 v38, vcc, 0xf0000, v0
	s_nop 1
	v_addc_co_u32_e32 v39, vcc, 0, v1, vcc
	global_load_dword v0, v[0:1], off nt
	s_nop 0
	global_load_dword v1, v[2:3], off nt
	s_nop 0
	global_load_dword v2, v[4:5], off nt
	global_load_dword v3, v[6:7], off nt
	s_nop 0
	global_load_dword v4, v[8:9], off nt
	global_load_dword v5, v[10:11], off nt
	global_load_dword v6, v[12:13], off nt
	global_load_dword v7, v[14:15], off nt
	s_nop 0
	global_load_dword v8, v[24:25], off nt
	global_load_dword v9, v[26:27], off nt
	global_load_dword v10, v[28:29], off nt
	global_load_dword v11, v[30:31], off nt
	global_load_dword v12, v[32:33], off nt
	global_load_dword v13, v[34:35], off nt
	global_load_dword v14, v[36:37], off nt
	global_load_dword v15, v[38:39], off nt
	s_branch .LBB0_110
.LBB0_113:
	s_waitcnt vmcnt(17)
	v_mov_b32_e32 v0, v208
	s_mov_b32 s37, s2
	s_barrier
	s_cmpk_gt_i32 s37, 0xaff
	s_cbranch_scc1 .Lcv_after_gu
	s_add_u32 s24, s46, 0x2c00000
	s_addc_u32 s26, s47, 0
	s_add_u32 s27, s56, 0x2c00000
	s_addc_u32 s36, s57, 0
	s_ashr_i32 s28, s37, 31
	s_lshr_b32 s28, s28, 28
	s_add_i32 s28, s37, s28
	s_ashr_i32 s29, s28, 4
	s_and_b32 s28, s28, 0x1fffff0
	s_lshl_b32 s40, s29, 6
	s_sub_i32 s41, s37, s28
	s_bitcmp0_b32 s29, 1
	s_cselect_b32 s42, s26, s36
	s_cselect_b32 s43, s24, s27
	s_ashr_i32 s28, s40, 1
	s_and_b32 s28, s28, 0xffffff80
	s_ashr_i32 s29, s28, 31
	v_and_b32_e32 v20, 63, v0
	s_lshl_b64 s[28:29], s[28:29], 2
	s_add_u32 s28, s43, s28
	s_waitcnt vmcnt(16)
	v_and_or_b32 v1, s40, 64, v20
	v_ashrrev_i32_e32 v24, 6, v0
	s_addc_u32 s29, s42, s29
	s_waitcnt vmcnt(3)
	v_lshlrev_b32_e32 v16, 2, v1
	v_lshl_add_u64 v[2:3], s[28:29], 0, v[16:17]
	v_lshl_add_u32 v1, s41, 7, v24
	s_movk_i32 s28, 0x5800
	v_mad_i64_i32 v[2:3], s[28:29], v1, s28, v[2:3]
	s_mov_b32 s28, 0x2c000
	s_nop 0
	v_add_co_u32_e32 v4, vcc, s28, v2
	s_mov_b32 s28, 0x58000
	s_nop 0
	v_addc_co_u32_e32 v5, vcc, 0, v3, vcc
	v_add_co_u32_e32 v6, vcc, s28, v2
	s_mov_b32 s28, 0x84000
	s_nop 0
	v_addc_co_u32_e32 v7, vcc, 0, v3, vcc
	v_add_co_u32_e32 v8, vcc, s28, v2
	s_mov_b32 s28, 0xb0000
	s_nop 0
	v_addc_co_u32_e32 v9, vcc, 0, v3, vcc
	v_add_co_u32_e32 v10, vcc, s28, v2
	s_mov_b32 s28, 0xdc000
	s_nop 0
	v_addc_co_u32_e32 v11, vcc, 0, v3, vcc
	v_add_co_u32_e32 v12, vcc, s28, v2
	s_mov_b32 s28, 0x108000
	s_nop 0
	v_addc_co_u32_e32 v13, vcc, 0, v3, vcc
	v_add_co_u32_e32 v14, vcc, s28, v2
	s_mov_b32 s28, 0x134000
	s_waitcnt vmcnt(2)
	v_addc_co_u32_e32 v15, vcc, 0, v3, vcc
	v_add_co_u32_e32 v26, vcc, s28, v2
	s_mov_b32 s28, 0x160000
	s_nop 0
	v_addc_co_u32_e32 v27, vcc, 0, v3, vcc
	v_add_co_u32_e32 v28, vcc, s28, v2
	s_mov_b32 s28, 0x18c000
	s_nop 0
	v_addc_co_u32_e32 v29, vcc, 0, v3, vcc
	v_add_co_u32_e32 v30, vcc, s28, v2
	s_mov_b32 s28, 0x1b8000
	s_nop 0
	v_addc_co_u32_e32 v31, vcc, 0, v3, vcc
	v_add_co_u32_e32 v32, vcc, s28, v2
	s_mov_b32 s28, 0x1e4000
	s_nop 0
	v_addc_co_u32_e32 v33, vcc, 0, v3, vcc
	v_add_co_u32_e32 v34, vcc, s28, v2
	s_mov_b32 s28, 0x210000
	s_nop 0
	v_addc_co_u32_e32 v35, vcc, 0, v3, vcc
	v_add_co_u32_e32 v36, vcc, s28, v2
	s_mov_b32 s28, 0x23c000
	s_nop 0
	v_addc_co_u32_e32 v37, vcc, 0, v3, vcc
	v_add_co_u32_e32 v38, vcc, s28, v2
	s_mov_b32 s28, 0x268000
	s_nop 0
	v_addc_co_u32_e32 v39, vcc, 0, v3, vcc
	v_add_co_u32_e32 v40, vcc, s28, v2
	s_load_dword s40, s[62:63], 0x0
	s_load_dword s28, s[62:63], 0x10
	v_ashrrev_i32_e32 v21, 4, v0
	v_lshlrev_b32_e32 v0, 3, v0
	v_addc_co_u32_e32 v41, vcc, 0, v3, vcc
	s_waitcnt lgkmcnt(0)
	s_lshr_b32 s28, s28, 16
	s_mov_b32 s29, 0x294000
	s_cmp_lg_u32 s28, 0
	v_and_b32_e32 v23, 0x78, v0
	v_add_co_u32_e32 v42, vcc, s29, v2
	s_cselect_b64 s[28:29], -1, 0
	v_lshlrev_b32_e32 v16, 1, v23
	s_cmp_lg_u64 s[28:29], 0
	v_lshl_add_u64 v[0:1], s[18:19], 0, v[16:17]
	s_mov_b64 s[28:29], 0x4378000
	v_addc_co_u32_e32 v43, vcc, 0, v3, vcc
	v_lshl_add_u64 v[18:19], v[0:1], 0, s[28:29]
	global_load_dword v0, v[2:3], off nt
	global_load_dword v1, v[4:5], off nt
	s_nop 0
	global_load_dword v2, v[6:7], off nt
	global_load_dword v3, v[8:9], off nt
	global_load_dword v4, v[10:11], off nt
	global_load_dword v5, v[12:13], off nt
	s_nop 0
	global_load_dword v6, v[14:15], off nt
	global_load_dword v7, v[26:27], off nt
	global_load_dword v8, v[28:29], off nt
	global_load_dword v9, v[30:31], off nt
	global_load_dword v10, v[32:33], off nt
	global_load_dword v11, v[34:35], off nt
	global_load_dword v12, v[36:37], off nt
	global_load_dword v13, v[38:39], off nt
	global_load_dword v14, v[40:41], off nt
	global_load_dword v15, v[42:43], off nt
	s_addc_u32 s42, s40, 0
	s_mov_b32 s42, s60
	s_movk_i32 s28, 0x104
	s_lshl_b32 s44, s42, 7
	v_mul_lo_u32 v22, v24, s28
	v_mul_u32_u24_e32 v23, 0x104, v23
	s_lshl_b32 s43, s37, 7
	v_add_u32_e32 v24, s44, v24
	s_mov_b64 s[40:41], 0
	s_branch .LBB0_116

.LBB0_125:
	s_waitcnt vmcnt(17)
	v_mov_b32_e32 v0, v208
	s_lshl_b32 s42, s24, 1
	s_sub_i32 s42, s2, s42
	s_sub_i32 s42, s42, 128
	s_cmp_gt_u32 s42, 1
	s_cbranch_scc1 .LBB0_124
	s_lshl_b64 s[28:29], s[24:25], 16
	s_add_u32 s28, s36, s28
	s_addc_u32 s29, s37, s29
	s_lshl_b64 s[40:41], s[24:25], 15
	s_add_u32 s40, s26, s40
	v_and_b32_e32 v22, 63, v0
	s_addc_u32 s41, s27, s41
	s_lshl_b32 s43, s42, 6
	s_waitcnt vmcnt(15)
	v_ashrrev_i32_e32 v2, 6, v0
	s_waitcnt vmcnt(13)
	v_or_b32_e32 v4, s43, v22
	s_waitcnt vmcnt(12)
	v_ashrrev_i32_e32 v5, 31, v4
	v_ashrrev_i32_e32 v3, 31, v2
	v_lshl_add_u64 v[4:5], v[4:5], 2, s[28:29]
	s_waitcnt vmcnt(10)
	v_lshlrev_b64 v[6:7], 9, v[2:3]
	v_lshl_add_u64 v[4:5], v[4:5], 0, v[6:7]
	s_movk_i32 s44, 0x2000
	v_add_co_u32_e32 v26, vcc, s44, v4
	s_movk_i32 s44, 0x6000
	s_nop 0
	v_addc_co_u32_e32 v27, vcc, 0, v5, vcc
	v_add_co_u32_e32 v28, vcc, s54, v4
	s_mov_b32 s45, 0xf000
	s_nop 0
	v_addc_co_u32_e32 v29, vcc, 0, v5, vcc
	v_add_co_u32_e32 v30, vcc, s44, v4
	s_mov_b32 s44, 0xa000
	s_nop 0
	v_addc_co_u32_e32 v31, vcc, 0, v5, vcc
	s_waitcnt vmcnt(9)
	v_add_co_u32_e32 v8, vcc, s78, v4
	v_ashrrev_i32_e32 v23, 4, v0
	s_waitcnt vmcnt(8)
	v_addc_co_u32_e32 v9, vcc, 0, v5, vcc
	s_waitcnt vmcnt(7)
	v_add_co_u32_e32 v10, vcc, s44, v4
	s_mov_b32 s44, 0xe000
	s_waitcnt vmcnt(6)
	v_addc_co_u32_e32 v11, vcc, 0, v5, vcc
	s_waitcnt vmcnt(5)
	v_add_co_u32_e32 v12, vcc, s16, v4
	v_lshlrev_b32_e32 v0, 3, v0
	s_waitcnt vmcnt(4)
	v_addc_co_u32_e32 v13, vcc, 0, v5, vcc
	s_waitcnt vmcnt(3)
	v_add_co_u32_e32 v14, vcc, s44, v4
	s_load_dword s46, s[62:63], 0x0
	s_load_dword s44, s[62:63], 0x10
	s_waitcnt vmcnt(2)
	v_addc_co_u32_e32 v15, vcc, 0, v5, vcc
	v_add_co_u32_e32 v32, vcc, s45, v4
	s_waitcnt lgkmcnt(0)
	s_lshr_b32 s44, s44, 16
	s_cmp_lg_u32 s44, 0
	s_cselect_b64 s[44:45], -1, 0
	v_cndmask_b32_e64 v1, 0, 1, s[44:45]
	s_cmp_lg_u64 s[44:45], 0
	v_and_b32_e32 v0, 0x78, v0
	s_addc_u32 s44, s46, 0
	v_lshlrev_b32_e32 v16, 1, v0
	v_mul_u32_u24_e32 v24, 0x104, v0
	v_lshl_add_u64 v[20:21], s[28:29], 0, v[6:7]
	s_lshl_b32 s28, s46, 6
	v_lshlrev_b32_e32 v0, 6, v1
	v_lshl_add_u64 v[18:19], s[40:41], 0, v[16:17]
	s_movk_i32 s40, 0x104
	v_add_u32_e32 v0, s28, v0
	v_addc_co_u32_e32 v33, vcc, 0, v5, vcc
	v_mul_lo_u32 v16, v2, s40
	v_or_b32_e32 v25, v0, v22
	global_load_dword v7, v[8:9], off offset:-4096 nt
	s_nop 0
	global_load_dword v8, v[8:9], off nt
	s_nop 0
	global_load_dword v9, v[10:11], off offset:-4096 nt
	s_nop 0
	global_load_dword v10, v[10:11], off nt
	s_nop 0
	global_load_dword v11, v[12:13], off offset:-4096 nt
	s_nop 0
	global_load_dword v12, v[12:13], off nt
	s_nop 0
	global_load_dword v13, v[14:15], off offset:-4096 nt
	s_nop 0
	global_load_dword v14, v[14:15], off nt
	s_nop 0
	global_load_dword v0, v[4:5], off nt
	global_load_dword v1, v[26:27], off offset:-4096 nt
	global_load_dword v2, v[26:27], off nt
	global_load_dword v3, v[28:29], off offset:-4096 nt
	s_nop 0
	global_load_dword v4, v[28:29], off nt
	global_load_dword v5, v[30:31], off offset:-4096 nt
	global_load_dword v6, v[30:31], off nt
	global_load_dword v15, v[32:33], off nt
	s_lshl_b32 s45, s44, 6
	s_mov_b64 s[40:41], 0
	s_branch .LBB0_128

.LBB0_128:
	s_and_b64 s[28:29], s[40:41], exec
	s_cselect_b32 s28, 0x8200, 0
	s_add_i32 s46, s28, 0
	s_add_i32 s42, s44, s42
	s_cmp_gt_i32 s42, 1
	v_lshlrev_b32_e32 v26, 2, v22
	s_cselect_b64 s[28:29], -1, 0
	v_add3_u32 v26, s46, v26, v16
	s_and_b64 vcc, exec, s[28:29]
	s_waitcnt vmcnt(7)
	ds_write_b32 v26, v0
	s_waitcnt vmcnt(6)
	ds_write_b32 v26, v1 offset:2080
	s_waitcnt vmcnt(5)
	ds_write_b32 v26, v2 offset:4160
	s_waitcnt vmcnt(4)
	ds_write_b32 v26, v3 offset:6240
	s_waitcnt vmcnt(3)
	ds_write_b32 v26, v4 offset:8320
	s_waitcnt vmcnt(2)
	ds_write_b32 v26, v5 offset:10400
	s_waitcnt vmcnt(1)
	ds_write_b32 v26, v6 offset:12480
	ds_write_b32 v26, v7 offset:14560
	ds_write_b32 v26, v8 offset:16640
	ds_write_b32 v26, v9 offset:18720
	ds_write_b32 v26, v10 offset:20800
	ds_write_b32 v26, v11 offset:22880
	ds_write_b32 v26, v12 offset:24960
	ds_write_b32 v26, v13 offset:27040
	ds_write_b32 v26, v14 offset:29120
	s_waitcnt vmcnt(0)
	ds_write_b32 v26, v15 offset:31200
	s_cbranch_vccnz .LBB0_127
	v_add_u32_e32 v0, s43, v25
	v_ashrrev_i32_e32 v1, 31, v0
	v_lshl_add_u64 v[0:1], v[0:1], 2, v[20:21]
	v_add_co_u32_e32 v2, vcc, 0x1000, v0
	s_nop 1
	v_addc_co_u32_e32 v3, vcc, 0, v1, vcc
	v_add_co_u32_e32 v4, vcc, 0x2000, v0
	s_nop 1
	v_addc_co_u32_e32 v5, vcc, 0, v1, vcc
	v_add_co_u32_e32 v6, vcc, 0x3000, v0
	s_nop 1
	v_addc_co_u32_e32 v7, vcc, 0, v1, vcc
	v_add_co_u32_e32 v8, vcc, s54, v0
	s_nop 1
	v_addc_co_u32_e32 v9, vcc, 0, v1, vcc
	v_add_co_u32_e32 v10, vcc, 0x5000, v0
	s_nop 1
	v_addc_co_u32_e32 v11, vcc, 0, v1, vcc
	v_add_co_u32_e32 v12, vcc, 0x6000, v0
	s_nop 1
	v_addc_co_u32_e32 v13, vcc, 0, v1, vcc
	v_add_co_u32_e32 v14, vcc, 0x7000, v0
	s_nop 1
	v_addc_co_u32_e32 v15, vcc, 0, v1, vcc
	v_add_co_u32_e32 v26, vcc, 0x8000, v0
	s_nop 1
	v_addc_co_u32_e32 v27, vcc, 0, v1, vcc
	v_add_co_u32_e32 v28, vcc, 0x9000, v0
	s_nop 1
	v_addc_co_u32_e32 v29, vcc, 0, v1, vcc
	v_add_co_u32_e32 v30, vcc, 0xa000, v0
	s_nop 1
	v_addc_co_u32_e32 v31, vcc, 0, v1, vcc
	v_add_co_u32_e32 v32, vcc, 0xb000, v0
	s_nop 1
	v_addc_co_u32_e32 v33, vcc, 0, v1, vcc
	v_add_co_u32_e32 v34, vcc, s16, v0
	s_nop 1
	v_addc_co_u32_e32 v35, vcc, 0, v1, vcc
	v_add_co_u32_e32 v36, vcc, 0xd000, v0
	s_nop 1
	v_addc_co_u32_e32 v37, vcc, 0, v1, vcc
	v_add_co_u32_e32 v38, vcc, 0xe000, v0
	s_nop 1
	v_addc_co_u32_e32 v39, vcc, 0, v1, vcc
	v_add_co_u32_e32 v40, vcc, 0xf000, v0
	s_nop 1
	v_addc_co_u32_e32 v41, vcc, 0, v1, vcc
	global_load_dword v0, v[0:1], off nt
	s_nop 0
	global_load_dword v1, v[2:3], off nt
	s_nop 0
	global_load_dword v2, v[4:5], off nt
	global_load_dword v3, v[6:7], off nt
	s_nop 0
	global_load_dword v4, v[8:9], off nt
	global_load_dword v5, v[10:11], off nt
	global_load_dword v6, v[12:13], off nt
	global_load_dword v7, v[14:15], off nt
	s_nop 0
	global_load_dword v8, v[26:27], off nt
	global_load_dword v9, v[28:29], off nt
	global_load_dword v10, v[30:31], off nt
	global_load_dword v11, v[32:33], off nt
	global_load_dword v12, v[34:35], off nt
	global_load_dword v13, v[36:37], off nt
	global_load_dword v14, v[38:39], off nt
	global_load_dword v15, v[40:41], off nt
	s_branch .LBB0_127

.LBB0_132:
	s_waitcnt vmcnt(17)
	v_mov_b32_e32 v0, v208
	s_lshl_b32 s41, s40, 1
	s_sub_i32 s41, s2, s41
	s_sub_i32 s41, s41, 136
	s_cmp_gt_u32 s41, 1
	s_cbranch_scc1 .LBB0_131
	s_lshl_b32 s24, s40, 14
	s_lshl_b64 s[28:29], s[24:25], 2
	s_add_u32 s28, s36, s28
	s_addc_u32 s29, s37, s29
	s_lshl_b32 s24, s40, 15
	s_add_u32 s38, s26, s24
	v_and_b32_e32 v22, 63, v0
	s_addc_u32 s39, s27, 0
	s_lshl_b32 s24, s41, 6
	s_waitcnt vmcnt(15)
	v_ashrrev_i32_e32 v2, 6, v0
	s_waitcnt vmcnt(13)
	v_or_b32_e32 v4, s24, v22
	s_waitcnt vmcnt(12)
	v_ashrrev_i32_e32 v5, 31, v4
	v_ashrrev_i32_e32 v3, 31, v2
	v_lshl_add_u64 v[4:5], v[4:5], 2, s[28:29]
	s_waitcnt vmcnt(10)
	v_lshlrev_b64 v[6:7], 9, v[2:3]
	v_lshl_add_u64 v[4:5], v[4:5], 0, v[6:7]
	s_movk_i32 s42, 0x2000
	v_add_co_u32_e32 v26, vcc, s42, v4
	s_movk_i32 s42, 0x6000
	s_nop 0
	v_addc_co_u32_e32 v27, vcc, 0, v5, vcc
	v_add_co_u32_e32 v28, vcc, s54, v4
	v_ashrrev_i32_e32 v23, 4, v0
	s_nop 0
	v_addc_co_u32_e32 v29, vcc, 0, v5, vcc
	v_add_co_u32_e32 v30, vcc, s42, v4
	s_mov_b32 s42, 0xa000
	s_nop 0
	v_addc_co_u32_e32 v31, vcc, 0, v5, vcc
	s_waitcnt vmcnt(9)
	v_add_co_u32_e32 v8, vcc, s78, v4
	v_lshlrev_b32_e32 v0, 3, v0
	s_waitcnt vmcnt(8)
	v_addc_co_u32_e32 v9, vcc, 0, v5, vcc
	s_waitcnt vmcnt(7)
	v_add_co_u32_e32 v10, vcc, s42, v4
	s_mov_b32 s42, 0xe000
	s_waitcnt vmcnt(6)
	v_addc_co_u32_e32 v11, vcc, 0, v5, vcc
	s_waitcnt vmcnt(5)
	v_add_co_u32_e32 v12, vcc, s16, v4
	s_mov_b32 s43, 0xf000
	s_waitcnt vmcnt(4)
	v_addc_co_u32_e32 v13, vcc, 0, v5, vcc
	s_waitcnt vmcnt(3)
	v_add_co_u32_e32 v14, vcc, s42, v4
	s_load_dword s44, s[62:63], 0x0
	s_load_dword s42, s[62:63], 0x10
	s_waitcnt vmcnt(2)
	v_addc_co_u32_e32 v15, vcc, 0, v5, vcc
	v_and_b32_e32 v20, 0x78, v0
	v_add_co_u32_e32 v32, vcc, s43, v4
	s_waitcnt lgkmcnt(0)
	s_lshr_b32 s42, s42, 16
	s_cmp_lg_u32 s42, 0
	s_cselect_b64 s[42:43], -1, 0
	v_lshlrev_b32_e32 v16, 1, v20
	v_cndmask_b32_e64 v3, 0, 1, s[42:43]
	s_cmp_lg_u64 s[42:43], 0
	v_lshl_add_u64 v[0:1], s[38:39], 0, v[16:17]
	s_mov_b64 s[38:39], 0x20000
	s_addc_u32 s42, s44, 0
	v_lshl_add_u64 v[18:19], v[0:1], 0, s[38:39]
	v_mul_u32_u24_e32 v24, 0x104, v20
	v_lshl_add_u64 v[20:21], s[28:29], 0, v[6:7]
	s_lshl_b32 s28, s44, 6
	v_lshlrev_b32_e32 v0, 6, v3
	s_movk_i32 s38, 0x104
	v_add_u32_e32 v0, s28, v0
	v_addc_co_u32_e32 v33, vcc, 0, v5, vcc
	v_mul_lo_u32 v16, v2, s38
	v_or_b32_e32 v25, v0, v22
	global_load_dword v7, v[8:9], off offset:-4096 nt
	s_nop 0
	global_load_dword v8, v[8:9], off nt
	s_nop 0
	global_load_dword v9, v[10:11], off offset:-4096 nt
	s_nop 0
	global_load_dword v10, v[10:11], off nt
	s_nop 0
	global_load_dword v11, v[12:13], off offset:-4096 nt
	s_nop 0
	global_load_dword v12, v[12:13], off nt
	s_nop 0
	global_load_dword v13, v[14:15], off offset:-4096 nt
	s_nop 0
	global_load_dword v14, v[14:15], off nt
	s_nop 0
	global_load_dword v0, v[4:5], off nt
	global_load_dword v1, v[26:27], off offset:-4096 nt
	global_load_dword v2, v[26:27], off nt
	global_load_dword v3, v[28:29], off offset:-4096 nt
	s_nop 0
	global_load_dword v4, v[28:29], off nt
	global_load_dword v5, v[30:31], off offset:-4096 nt
	global_load_dword v6, v[30:31], off nt
	global_load_dword v15, v[32:33], off nt
	s_lshl_b32 s43, s42, 6
	s_mov_b64 s[38:39], 0
	s_branch .LBB0_135

.LBB0_135:
	s_and_b64 s[28:29], s[38:39], exec
	s_cselect_b32 s28, 0x8200, 0
	s_add_i32 s44, s28, 0
	s_add_i32 s41, s42, s41
	s_cmp_gt_i32 s41, 1
	v_lshlrev_b32_e32 v26, 2, v22
	s_cselect_b64 s[28:29], -1, 0
	v_add3_u32 v26, s44, v26, v16
	s_and_b64 vcc, exec, s[28:29]
	s_waitcnt vmcnt(7)
	ds_write_b32 v26, v0
	s_waitcnt vmcnt(6)
	ds_write_b32 v26, v1 offset:2080
	s_waitcnt vmcnt(5)
	ds_write_b32 v26, v2 offset:4160
	s_waitcnt vmcnt(4)
	ds_write_b32 v26, v3 offset:6240
	s_waitcnt vmcnt(3)
	ds_write_b32 v26, v4 offset:8320
	s_waitcnt vmcnt(2)
	ds_write_b32 v26, v5 offset:10400
	s_waitcnt vmcnt(1)
	ds_write_b32 v26, v6 offset:12480
	ds_write_b32 v26, v7 offset:14560
	ds_write_b32 v26, v8 offset:16640
	ds_write_b32 v26, v9 offset:18720
	ds_write_b32 v26, v10 offset:20800
	ds_write_b32 v26, v11 offset:22880
	ds_write_b32 v26, v12 offset:24960
	ds_write_b32 v26, v13 offset:27040
	ds_write_b32 v26, v14 offset:29120
	s_waitcnt vmcnt(0)
	ds_write_b32 v26, v15 offset:31200
	s_cbranch_vccnz .LBB0_134
	v_add_u32_e32 v0, s24, v25
	v_ashrrev_i32_e32 v1, 31, v0
	v_lshl_add_u64 v[0:1], v[0:1], 2, v[20:21]
	v_add_co_u32_e32 v2, vcc, 0x1000, v0
	s_nop 1
	v_addc_co_u32_e32 v3, vcc, 0, v1, vcc
	v_add_co_u32_e32 v4, vcc, 0x2000, v0
	s_nop 1
	v_addc_co_u32_e32 v5, vcc, 0, v1, vcc
	v_add_co_u32_e32 v6, vcc, 0x3000, v0
	s_nop 1
	v_addc_co_u32_e32 v7, vcc, 0, v1, vcc
	v_add_co_u32_e32 v8, vcc, s54, v0
	s_nop 1
	v_addc_co_u32_e32 v9, vcc, 0, v1, vcc
	v_add_co_u32_e32 v10, vcc, 0x5000, v0
	s_nop 1
	v_addc_co_u32_e32 v11, vcc, 0, v1, vcc
	v_add_co_u32_e32 v12, vcc, 0x6000, v0
	s_nop 1
	v_addc_co_u32_e32 v13, vcc, 0, v1, vcc
	v_add_co_u32_e32 v14, vcc, 0x7000, v0
	s_nop 1
	v_addc_co_u32_e32 v15, vcc, 0, v1, vcc
	v_add_co_u32_e32 v26, vcc, 0x8000, v0
	s_nop 1
	v_addc_co_u32_e32 v27, vcc, 0, v1, vcc
	v_add_co_u32_e32 v28, vcc, 0x9000, v0
	s_nop 1
	v_addc_co_u32_e32 v29, vcc, 0, v1, vcc
	v_add_co_u32_e32 v30, vcc, 0xa000, v0
	s_nop 1
	v_addc_co_u32_e32 v31, vcc, 0, v1, vcc
	v_add_co_u32_e32 v32, vcc, 0xb000, v0
	s_nop 1
	v_addc_co_u32_e32 v33, vcc, 0, v1, vcc
	v_add_co_u32_e32 v34, vcc, s16, v0
	s_nop 1
	v_addc_co_u32_e32 v35, vcc, 0, v1, vcc
	v_add_co_u32_e32 v36, vcc, 0xd000, v0
	s_nop 1
	v_addc_co_u32_e32 v37, vcc, 0, v1, vcc
	v_add_co_u32_e32 v38, vcc, 0xe000, v0
	s_nop 1
	v_addc_co_u32_e32 v39, vcc, 0, v1, vcc
	v_add_co_u32_e32 v40, vcc, 0xf000, v0
	s_nop 1
	v_addc_co_u32_e32 v41, vcc, 0, v1, vcc
	global_load_dword v0, v[0:1], off nt
	s_nop 0
	global_load_dword v1, v[2:3], off nt
	s_nop 0
	global_load_dword v2, v[4:5], off nt
	global_load_dword v3, v[6:7], off nt
	s_nop 0
	global_load_dword v4, v[8:9], off nt
	global_load_dword v5, v[10:11], off nt
	global_load_dword v6, v[12:13], off nt
	global_load_dword v7, v[14:15], off nt
	s_nop 0
	global_load_dword v8, v[26:27], off nt
	global_load_dword v9, v[28:29], off nt
	global_load_dword v10, v[30:31], off nt
	global_load_dword v11, v[32:33], off nt
	global_load_dword v12, v[34:35], off nt
	global_load_dword v13, v[36:37], off nt
	global_load_dword v14, v[38:39], off nt
	global_load_dword v15, v[40:41], off nt
	s_branch .LBB0_134

.LBB0_139:
	s_waitcnt vmcnt(17)
	v_mov_b32_e32 v0, v208
	s_lshl_b32 s39, s38, 1
	s_sub_i32 s39, s2, s39
	s_sub_i32 s39, s39, 152
	s_cmp_gt_u32 s39, 1
	s_cbranch_scc1 .LBB0_138
	s_lshl_b32 s24, s38, 14
	s_lshl_b64 s[22:23], s[24:25], 2
	s_add_u32 s22, s36, s22
	s_addc_u32 s23, s37, s23
	s_lshl_b32 s24, s38, 15
	s_add_u32 s28, s26, s24
	v_and_b32_e32 v22, 63, v0
	s_addc_u32 s29, s27, 0
	s_lshl_b32 s24, s39, 6
	s_waitcnt vmcnt(15)
	v_ashrrev_i32_e32 v2, 6, v0
	s_waitcnt vmcnt(13)
	v_or_b32_e32 v4, s24, v22
	s_waitcnt vmcnt(12)
	v_ashrrev_i32_e32 v5, 31, v4
	v_ashrrev_i32_e32 v3, 31, v2
	v_lshl_add_u64 v[4:5], v[4:5], 2, s[22:23]
	s_waitcnt vmcnt(10)
	v_lshlrev_b64 v[6:7], 9, v[2:3]
	v_lshl_add_u64 v[4:5], v[4:5], 0, v[6:7]
	s_movk_i32 s40, 0x2000
	v_add_co_u32_e32 v26, vcc, s40, v4
	s_movk_i32 s40, 0x6000
	s_nop 0
	v_addc_co_u32_e32 v27, vcc, 0, v5, vcc
	v_add_co_u32_e32 v28, vcc, s54, v4
	v_ashrrev_i32_e32 v23, 4, v0
	s_nop 0
	v_addc_co_u32_e32 v29, vcc, 0, v5, vcc
	v_add_co_u32_e32 v30, vcc, s40, v4
	s_mov_b32 s40, 0xa000
	s_nop 0
	v_addc_co_u32_e32 v31, vcc, 0, v5, vcc
	s_waitcnt vmcnt(9)
	v_add_co_u32_e32 v8, vcc, s78, v4
	v_lshlrev_b32_e32 v0, 3, v0
	s_waitcnt vmcnt(8)
	v_addc_co_u32_e32 v9, vcc, 0, v5, vcc
	s_waitcnt vmcnt(7)
	v_add_co_u32_e32 v10, vcc, s40, v4
	s_mov_b32 s40, 0xe000
	s_waitcnt vmcnt(6)
	v_addc_co_u32_e32 v11, vcc, 0, v5, vcc
	s_waitcnt vmcnt(5)
	v_add_co_u32_e32 v12, vcc, s16, v4
	s_mov_b32 s41, 0xf000
	s_waitcnt vmcnt(4)
	v_addc_co_u32_e32 v13, vcc, 0, v5, vcc
	s_waitcnt vmcnt(3)
	v_add_co_u32_e32 v14, vcc, s40, v4
	s_load_dword s42, s[62:63], 0x0
	s_load_dword s40, s[62:63], 0x10
	s_waitcnt vmcnt(2)
	v_addc_co_u32_e32 v15, vcc, 0, v5, vcc
	v_and_b32_e32 v20, 0x78, v0
	v_add_co_u32_e32 v32, vcc, s41, v4
	s_waitcnt lgkmcnt(0)
	s_lshr_b32 s40, s40, 16
	s_cmp_lg_u32 s40, 0
	s_cselect_b64 s[40:41], -1, 0
	v_lshlrev_b32_e32 v16, 1, v20
	v_cndmask_b32_e64 v3, 0, 1, s[40:41]
	s_cmp_lg_u64 s[40:41], 0
	v_lshl_add_u64 v[0:1], s[28:29], 0, v[16:17]
	s_mov_b64 s[28:29], 0x60000
	s_addc_u32 s40, s42, 0
	v_lshl_add_u64 v[18:19], v[0:1], 0, s[28:29]
	v_mul_u32_u24_e32 v24, 0x104, v20
	v_lshl_add_u64 v[20:21], s[22:23], 0, v[6:7]
	s_lshl_b32 s22, s42, 6
	v_lshlrev_b32_e32 v0, 6, v3
	s_movk_i32 s28, 0x104
	v_add_u32_e32 v0, s22, v0
	v_addc_co_u32_e32 v33, vcc, 0, v5, vcc
	v_mul_lo_u32 v16, v2, s28
	v_or_b32_e32 v25, v0, v22
	global_load_dword v7, v[8:9], off offset:-4096 nt
	s_nop 0
	global_load_dword v8, v[8:9], off nt
	s_nop 0
	global_load_dword v9, v[10:11], off offset:-4096 nt
	s_nop 0
	global_load_dword v10, v[10:11], off nt
	s_nop 0
	global_load_dword v11, v[12:13], off offset:-4096 nt
	s_nop 0
	global_load_dword v12, v[12:13], off nt
	s_nop 0
	global_load_dword v13, v[14:15], off offset:-4096 nt
	s_nop 0
	global_load_dword v14, v[14:15], off nt
	s_nop 0
	global_load_dword v0, v[4:5], off nt
	global_load_dword v1, v[26:27], off offset:-4096 nt
	global_load_dword v2, v[26:27], off nt
	global_load_dword v3, v[28:29], off offset:-4096 nt
	s_nop 0
	global_load_dword v4, v[28:29], off nt
	global_load_dword v5, v[30:31], off offset:-4096 nt
	global_load_dword v6, v[30:31], off nt
	global_load_dword v15, v[32:33], off nt
	s_lshl_b32 s41, s40, 6
	s_mov_b64 s[22:23], 0
	s_branch .LBB0_142

.LBB0_142:
	s_and_b64 s[28:29], s[22:23], exec
	s_cselect_b32 s28, 0x8200, 0
	s_add_i32 s42, s28, 0
	s_add_i32 s39, s40, s39
	s_cmp_gt_i32 s39, 1
	v_lshlrev_b32_e32 v26, 2, v22
	s_cselect_b64 s[28:29], -1, 0
	v_add3_u32 v26, s42, v26, v16
	s_and_b64 vcc, exec, s[28:29]
	s_waitcnt vmcnt(7)
	ds_write_b32 v26, v0
	s_waitcnt vmcnt(6)
	ds_write_b32 v26, v1 offset:2080
	s_waitcnt vmcnt(5)
	ds_write_b32 v26, v2 offset:4160
	s_waitcnt vmcnt(4)
	ds_write_b32 v26, v3 offset:6240
	s_waitcnt vmcnt(3)
	ds_write_b32 v26, v4 offset:8320
	s_waitcnt vmcnt(2)
	ds_write_b32 v26, v5 offset:10400
	s_waitcnt vmcnt(1)
	ds_write_b32 v26, v6 offset:12480
	ds_write_b32 v26, v7 offset:14560
	ds_write_b32 v26, v8 offset:16640
	ds_write_b32 v26, v9 offset:18720
	ds_write_b32 v26, v10 offset:20800
	ds_write_b32 v26, v11 offset:22880
	ds_write_b32 v26, v12 offset:24960
	ds_write_b32 v26, v13 offset:27040
	ds_write_b32 v26, v14 offset:29120
	s_waitcnt vmcnt(0)
	ds_write_b32 v26, v15 offset:31200
	s_cbranch_vccnz .LBB0_141
	v_add_u32_e32 v0, s24, v25
	v_ashrrev_i32_e32 v1, 31, v0
	v_lshl_add_u64 v[0:1], v[0:1], 2, v[20:21]
	v_add_co_u32_e32 v2, vcc, 0x1000, v0
	s_nop 1
	v_addc_co_u32_e32 v3, vcc, 0, v1, vcc
	v_add_co_u32_e32 v4, vcc, 0x2000, v0
	s_nop 1
	v_addc_co_u32_e32 v5, vcc, 0, v1, vcc
	v_add_co_u32_e32 v6, vcc, 0x3000, v0
	s_nop 1
	v_addc_co_u32_e32 v7, vcc, 0, v1, vcc
	v_add_co_u32_e32 v8, vcc, s54, v0
	s_nop 1
	v_addc_co_u32_e32 v9, vcc, 0, v1, vcc
	v_add_co_u32_e32 v10, vcc, 0x5000, v0
	s_nop 1
	v_addc_co_u32_e32 v11, vcc, 0, v1, vcc
	v_add_co_u32_e32 v12, vcc, 0x6000, v0
	s_nop 1
	v_addc_co_u32_e32 v13, vcc, 0, v1, vcc
	v_add_co_u32_e32 v14, vcc, 0x7000, v0
	s_nop 1
	v_addc_co_u32_e32 v15, vcc, 0, v1, vcc
	v_add_co_u32_e32 v26, vcc, 0x8000, v0
	s_nop 1
	v_addc_co_u32_e32 v27, vcc, 0, v1, vcc
	v_add_co_u32_e32 v28, vcc, 0x9000, v0
	s_nop 1
	v_addc_co_u32_e32 v29, vcc, 0, v1, vcc
	v_add_co_u32_e32 v30, vcc, 0xa000, v0
	s_nop 1
	v_addc_co_u32_e32 v31, vcc, 0, v1, vcc
	v_add_co_u32_e32 v32, vcc, 0xb000, v0
	s_nop 1
	v_addc_co_u32_e32 v33, vcc, 0, v1, vcc
	v_add_co_u32_e32 v34, vcc, s16, v0
	s_nop 1
	v_addc_co_u32_e32 v35, vcc, 0, v1, vcc
	v_add_co_u32_e32 v36, vcc, 0xd000, v0
	s_nop 1
	v_addc_co_u32_e32 v37, vcc, 0, v1, vcc
	v_add_co_u32_e32 v38, vcc, 0xe000, v0
	s_nop 1
	v_addc_co_u32_e32 v39, vcc, 0, v1, vcc
	v_add_co_u32_e32 v40, vcc, 0xf000, v0
	s_nop 1
	v_addc_co_u32_e32 v41, vcc, 0, v1, vcc
	global_load_dword v0, v[0:1], off nt
	s_nop 0
	global_load_dword v1, v[2:3], off nt
	s_nop 0
	global_load_dword v2, v[4:5], off nt
	global_load_dword v3, v[6:7], off nt
	s_nop 0
	global_load_dword v4, v[8:9], off nt
	global_load_dword v5, v[10:11], off nt
	global_load_dword v6, v[12:13], off nt
	global_load_dword v7, v[14:15], off nt
	s_nop 0
	global_load_dword v8, v[26:27], off nt
	global_load_dword v9, v[28:29], off nt
	global_load_dword v10, v[30:31], off nt
	global_load_dword v11, v[32:33], off nt
	global_load_dword v12, v[34:35], off nt
	global_load_dword v13, v[36:37], off nt
	global_load_dword v14, v[38:39], off nt
	global_load_dword v15, v[40:41], off nt
	s_branch .LBB0_141
